# al1 + nt hint on P0's bf16 weight-copy stores (28 store sites)
# speedup vs baseline: 1.0041x; 1.0041x over previous
.LBB0_106:
	v_mul_hi_i32 v3, v7, s38
	v_lshrrev_b32_e32 v4, 31, v3
	v_ashrrev_i32_e32 v3, 10, v3
	v_add_u32_e32 v12, v3, v4
	v_mul_i32_i24_e32 v3, 0x5b10, v12
	v_sub_u32_e32 v3, v7, v3
	v_cmp_lt_i32_e32 vcc, s39, v3
	s_and_saveexec_b64 s[24:25], vcc
	s_xor_b64 s[24:25], exec, s[24:25]
	s_cbranch_execz .LBB0_140
	v_cmp_lt_u32_e32 vcc, s40, v3
	s_and_saveexec_b64 s[26:27], vcc
	s_xor_b64 s[26:27], exec, s[26:27]
	s_cbranch_execz .LBB0_135
	v_cmp_lt_u32_e32 vcc, s41, v3
	s_and_saveexec_b64 s[28:29], vcc
	s_xor_b64 s[28:29], exec, s[28:29]
	s_cbranch_execz .LBB0_130
	v_cmp_lt_u32_e32 vcc, s42, v3
	s_and_saveexec_b64 s[30:31], vcc
	s_xor_b64 s[30:31], exec, s[30:31]
	s_cbranch_execz .LBB0_125
	v_cmp_lt_u32_e32 vcc, s43, v3
	s_and_saveexec_b64 s[34:35], vcc
	s_xor_b64 s[34:35], exec, s[34:35]
	s_cbranch_execz .LBB0_120
	v_cmp_lt_u32_e32 vcc, s44, v3
	s_and_saveexec_b64 s[36:37], vcc
	s_xor_b64 s[36:37], exec, s[36:37]
	s_cbranch_execz .LBB0_115
	s_load_dwordx2 s[58:59], s[6:7], 0x60
	v_add_u32_e32 v3, 0xffffa530, v3
	v_ashrrev_i32_e32 v13, 31, v12
	v_lshlrev_b32_e32 v4, 5, v3
	v_lshlrev_b64 v[14:15], 19, v[12:13]
	v_and_b32_e32 v11, 0x3e0, v4
	s_waitcnt lgkmcnt(0)
	v_lshl_add_u64 v[16:17], s[58:59], 0, v[14:15]
	v_lshlrev_b32_e32 v3, 1, v3
	v_lshlrev_b32_e32 v4, 2, v11
	v_and_b32_e32 v14, 0x7fffffc0, v3
	v_lshl_add_u64 v[16:17], v[16:17], 0, v[4:5]
	v_mov_b32_e32 v9, v5
	s_mov_b32 s58, 1
	v_lshl_add_u64 v[16:17], v[16:17], 0, v[8:9]
	v_mov_b32_e32 v3, v14
	s_mov_b32 s59, 0
	s_mov_b32 s60, 32
	v_mov_b32_e32 v105, v5
	s_lshl_b32 s61, s58, 1
	s_lshl_b32 s62, s59, 1
	v_or_b32_e32 v113, s62, v2
	s_add_i32 s63, s61, 4
	s_add_i32 s64, s62, 4
	s_add_i32 s66, s62, 8
	v_add_u32_e32 v104, v113, v14
	v_or_b32_e32 v115, s63, v1
	v_or_b32_e32 v129, s64, v2
	v_mov_b32_e32 v131, v5
	v_or_b32_e32 v109, s61, v1
	s_add_i32 s68, s62, 12
	v_or_b32_e32 v151, s66, v2
	v_lshlrev_b64 v[144:145], 12, v[104:105]
	v_add_u32_e32 v130, v115, v3
	v_add_u32_e32 v104, v129, v14
	v_mov_b32_e32 v119, v5
	s_add_i32 s65, s61, 8
	s_add_i32 s67, s61, 12
	s_add_i32 s70, s62, 16
	v_add_u32_e32 v118, v109, v3
	v_or_b32_e32 v153, s68, v2
	v_lshlrev_b64 v[130:131], 12, v[130:131]
	v_lshlrev_b64 v[146:147], 12, v[104:105]
	v_add_u32_e32 v104, v151, v14
	s_add_i32 s72, s62, 20
	v_or_b32_e32 v150, s65, v1
	v_or_b32_e32 v152, s67, v1
	v_or_b32_e32 v155, s70, v2
	v_lshlrev_b64 v[118:119], 12, v[118:119]
	v_lshl_add_u64 v[144:145], v[16:17], 0, v[144:145]
	v_lshl_add_u64 v[130:131], v[16:17], 0, v[130:131]
	v_lshlrev_b64 v[148:149], 12, v[104:105]
	v_add_u32_e32 v104, v153, v14
	v_mov_b32_e32 v133, v5
	v_mov_b32_e32 v135, v5
	s_add_i32 s69, s61, 16
	s_add_i32 s71, s61, 20
	s_add_i32 s74, s62, 24
	v_or_b32_e32 v157, s72, v2
	v_add_u32_e32 v132, v150, v3
	v_add_u32_e32 v134, v152, v3
	v_lshl_add_u64 v[118:119], v[16:17], 0, v[118:119]
	v_lshl_add_u64 v[146:147], v[16:17], 0, v[146:147]
	global_load_dword v162, v[144:145], off nt
	global_load_dword v163, v[118:119], off nt
	global_load_dword v164, v[146:147], off nt
	global_load_dword v165, v[130:131], off nt
	v_lshlrev_b64 v[130:131], 12, v[104:105]
	v_add_u32_e32 v104, v155, v14
	s_add_i32 s73, s61, 24
	s_add_i32 s61, s61, 28
	s_add_i32 s62, s62, 28
	v_or_b32_e32 v154, s69, v1
	v_or_b32_e32 v156, s71, v1
	v_or_b32_e32 v159, s74, v2
	v_lshlrev_b64 v[132:133], 12, v[132:133]
	v_lshlrev_b64 v[134:135], 12, v[134:135]
	v_lshl_add_u64 v[118:119], v[16:17], 0, v[148:149]
	v_lshl_add_u64 v[130:131], v[16:17], 0, v[130:131]
	v_lshlrev_b64 v[144:145], 12, v[104:105]
	v_add_u32_e32 v104, v157, v14
	v_mov_b32_e32 v137, v5
	v_mov_b32_e32 v139, v5
	v_or_b32_e32 v158, s73, v1
	v_or_b32_e32 v160, s61, v1
	v_or_b32_e32 v161, s62, v2
	v_add_u32_e32 v136, v154, v3
	v_add_u32_e32 v138, v156, v3
	v_lshl_add_u64 v[132:133], v[16:17], 0, v[132:133]
	v_lshl_add_u64 v[134:135], v[16:17], 0, v[134:135]
	global_load_dword v166, v[118:119], off nt
	global_load_dword v167, v[132:133], off nt
	global_load_dword v168, v[130:131], off nt
	global_load_dword v169, v[134:135], off nt
	v_lshlrev_b64 v[130:131], 12, v[104:105]
	v_add_u32_e32 v104, v159, v14
	v_mov_b32_e32 v141, v5
	v_mov_b32_e32 v143, v5
	v_add_u32_e32 v140, v158, v3
	v_add_u32_e32 v142, v160, v3
	v_lshlrev_b64 v[136:137], 12, v[136:137]
	v_lshlrev_b64 v[138:139], 12, v[138:139]
	v_lshl_add_u64 v[118:119], v[16:17], 0, v[144:145]
	v_lshl_add_u64 v[130:131], v[16:17], 0, v[130:131]
	v_lshlrev_b64 v[132:133], 12, v[104:105]
	v_add_u32_e32 v104, v161, v14
	v_lshlrev_b64 v[140:141], 12, v[140:141]
	v_lshlrev_b64 v[142:143], 12, v[142:143]
	v_lshl_add_u64 v[136:137], v[16:17], 0, v[136:137]
	v_lshl_add_u64 v[138:139], v[16:17], 0, v[138:139]
	global_load_dword v170, v[118:119], off nt
	global_load_dword v171, v[136:137], off nt
	global_load_dword v172, v[130:131], off nt
	global_load_dword v173, v[138:139], off nt
	v_lshl_add_u64 v[118:119], v[16:17], 0, v[132:133]
	v_lshlrev_b64 v[130:131], 12, v[104:105]
	v_lshl_add_u64 v[140:141], v[16:17], 0, v[140:141]
	v_lshl_add_u64 v[142:143], v[16:17], 0, v[142:143]
	v_lshl_add_u64 v[130:131], v[16:17], 0, v[130:131]
	global_load_dword v104, v[118:119], off nt
	global_load_dword v174, v[140:141], off nt
	global_load_dword v175, v[130:131], off nt
	global_load_dword v176, v[142:143], off nt
	s_add_i32 s59, s59, 16
	s_add_i32 s58, s58, 16
	s_add_i32 s60, s60, -16
	v_mad_u64_u32 v[118:119], s[62:63], v113, s33, v[6:7]
	v_mad_u64_u32 v[130:131], s[62:63], v109, s33, v[6:7]
	v_mad_u64_u32 v[132:133], s[62:63], v129, s33, v[6:7]
	v_mad_u64_u32 v[134:135], s[62:63], v115, s33, v[6:7]
	v_mad_u64_u32 v[136:137], s[62:63], v151, s33, v[6:7]
	v_mad_u64_u32 v[138:139], s[62:63], v150, s33, v[6:7]
	v_mad_u64_u32 v[140:141], s[62:63], v153, s33, v[6:7]
	v_mad_u64_u32 v[142:143], s[62:63], v152, s33, v[6:7]
	v_mad_u64_u32 v[144:145], s[62:63], v155, s33, v[6:7]
	v_mad_u64_u32 v[146:147], s[62:63], v154, s33, v[6:7]
	v_mad_u64_u32 v[148:149], s[62:63], v157, s33, v[6:7]
	v_mad_u64_u32 v[150:151], s[62:63], v156, s33, v[6:7]
	v_mad_u64_u32 v[152:153], s[62:63], v159, s33, v[6:7]
	v_mad_u64_u32 v[154:155], s[62:63], v158, s33, v[6:7]
	v_mad_u64_u32 v[156:157], s[62:63], v161, s33, v[6:7]
	v_mad_u64_u32 v[158:159], s[62:63], v160, s33, v[6:7]
	s_lshl_b32 s61, s58, 1
	s_lshl_b32 s62, s59, 1
	v_or_b32_e32 v13, s62, v2
	s_add_i32 s63, s61, 4
	s_add_i32 s64, s62, 4
	s_add_i32 s66, s62, 8
	v_add_u32_e32 v4, v13, v14
	v_or_b32_e32 v15, s63, v1
	v_or_b32_e32 v29, s64, v2
	v_mov_b32_e32 v31, v5
	v_or_b32_e32 v9, s61, v1
	s_add_i32 s68, s62, 12
	v_or_b32_e32 v51, s66, v2
	v_lshlrev_b64 v[44:45], 12, v[4:5]
	v_add_u32_e32 v30, v15, v3
	v_add_u32_e32 v4, v29, v14
	v_mov_b32_e32 v19, v5
	s_add_i32 s65, s61, 8
	s_add_i32 s67, s61, 12
	s_add_i32 s70, s62, 16
	v_add_u32_e32 v18, v9, v3
	v_or_b32_e32 v53, s68, v2
	v_lshlrev_b64 v[30:31], 12, v[30:31]
	v_lshlrev_b64 v[46:47], 12, v[4:5]
	v_add_u32_e32 v4, v51, v14
	s_add_i32 s72, s62, 20
	v_or_b32_e32 v50, s65, v1
	v_or_b32_e32 v52, s67, v1
	v_or_b32_e32 v55, s70, v2
	v_lshlrev_b64 v[18:19], 12, v[18:19]
	v_lshl_add_u64 v[44:45], v[16:17], 0, v[44:45]
	v_lshl_add_u64 v[30:31], v[16:17], 0, v[30:31]
	v_lshlrev_b64 v[48:49], 12, v[4:5]
	v_add_u32_e32 v4, v53, v14
	v_mov_b32_e32 v33, v5
	v_mov_b32_e32 v35, v5
	s_add_i32 s69, s61, 16
	s_add_i32 s71, s61, 20
	s_add_i32 s74, s62, 24
	v_or_b32_e32 v57, s72, v2
	v_add_u32_e32 v32, v50, v3
	v_add_u32_e32 v34, v52, v3
	v_lshl_add_u64 v[18:19], v[16:17], 0, v[18:19]
	v_lshl_add_u64 v[46:47], v[16:17], 0, v[46:47]
	global_load_dword v62, v[44:45], off nt
	global_load_dword v63, v[18:19], off nt
	global_load_dword v64, v[46:47], off nt
	global_load_dword v65, v[30:31], off nt
	v_lshlrev_b64 v[30:31], 12, v[4:5]
	v_add_u32_e32 v4, v55, v14
	s_add_i32 s73, s61, 24
	s_add_i32 s61, s61, 28
	s_add_i32 s62, s62, 28
	v_or_b32_e32 v54, s69, v1
	v_or_b32_e32 v56, s71, v1
	v_or_b32_e32 v59, s74, v2
	v_lshlrev_b64 v[32:33], 12, v[32:33]
	v_lshlrev_b64 v[34:35], 12, v[34:35]
	v_lshl_add_u64 v[18:19], v[16:17], 0, v[48:49]
	v_lshl_add_u64 v[30:31], v[16:17], 0, v[30:31]
	v_lshlrev_b64 v[44:45], 12, v[4:5]
	v_add_u32_e32 v4, v57, v14
	v_mov_b32_e32 v37, v5
	v_mov_b32_e32 v39, v5
	v_or_b32_e32 v58, s73, v1
	v_or_b32_e32 v60, s61, v1
	v_or_b32_e32 v61, s62, v2
	v_add_u32_e32 v36, v54, v3
	v_add_u32_e32 v38, v56, v3
	v_lshl_add_u64 v[32:33], v[16:17], 0, v[32:33]
	v_lshl_add_u64 v[34:35], v[16:17], 0, v[34:35]
	global_load_dword v66, v[18:19], off nt
	global_load_dword v67, v[32:33], off nt
	global_load_dword v68, v[30:31], off nt
	global_load_dword v69, v[34:35], off nt
	v_lshlrev_b64 v[30:31], 12, v[4:5]
	v_add_u32_e32 v4, v59, v14
	v_mov_b32_e32 v41, v5
	v_mov_b32_e32 v43, v5
	v_add_u32_e32 v40, v58, v3
	v_add_u32_e32 v42, v60, v3
	v_lshlrev_b64 v[36:37], 12, v[36:37]
	v_lshlrev_b64 v[38:39], 12, v[38:39]
	v_lshl_add_u64 v[18:19], v[16:17], 0, v[44:45]
	v_lshl_add_u64 v[30:31], v[16:17], 0, v[30:31]
	v_lshlrev_b64 v[32:33], 12, v[4:5]
	v_add_u32_e32 v4, v61, v14
	v_lshlrev_b64 v[40:41], 12, v[40:41]
	v_lshlrev_b64 v[42:43], 12, v[42:43]
	v_lshl_add_u64 v[36:37], v[16:17], 0, v[36:37]
	v_lshl_add_u64 v[38:39], v[16:17], 0, v[38:39]
	global_load_dword v70, v[18:19], off nt
	global_load_dword v71, v[36:37], off nt
	global_load_dword v72, v[30:31], off nt
	global_load_dword v73, v[38:39], off nt
	v_lshl_add_u64 v[18:19], v[16:17], 0, v[32:33]
	v_lshlrev_b64 v[30:31], 12, v[4:5]
	v_lshl_add_u64 v[40:41], v[16:17], 0, v[40:41]
	v_lshl_add_u64 v[42:43], v[16:17], 0, v[42:43]
	v_lshl_add_u64 v[30:31], v[16:17], 0, v[30:31]
	global_load_dword v4, v[18:19], off nt
	global_load_dword v74, v[40:41], off nt
	global_load_dword v75, v[30:31], off nt
	global_load_dword v76, v[42:43], off nt
	s_add_i32 s59, s59, 16
	s_add_i32 s58, s58, 16
	s_add_i32 s60, s60, -16
	v_mad_u64_u32 v[18:19], s[62:63], v13, s33, v[6:7]
	v_mad_u64_u32 v[30:31], s[62:63], v9, s33, v[6:7]
	v_mad_u64_u32 v[32:33], s[62:63], v29, s33, v[6:7]
	v_mad_u64_u32 v[34:35], s[62:63], v15, s33, v[6:7]
	v_mad_u64_u32 v[36:37], s[62:63], v51, s33, v[6:7]
	v_mad_u64_u32 v[38:39], s[62:63], v50, s33, v[6:7]
	v_mad_u64_u32 v[40:41], s[62:63], v53, s33, v[6:7]
	v_mad_u64_u32 v[42:43], s[62:63], v52, s33, v[6:7]
	v_mad_u64_u32 v[44:45], s[62:63], v55, s33, v[6:7]
	v_mad_u64_u32 v[46:47], s[62:63], v54, s33, v[6:7]
	v_mad_u64_u32 v[48:49], s[62:63], v57, s33, v[6:7]
	v_mad_u64_u32 v[50:51], s[62:63], v56, s33, v[6:7]
	v_mad_u64_u32 v[52:53], s[62:63], v59, s33, v[6:7]
	v_mad_u64_u32 v[54:55], s[62:63], v58, s33, v[6:7]
	v_mad_u64_u32 v[56:57], s[62:63], v61, s33, v[6:7]
	v_mad_u64_u32 v[58:59], s[62:63], v60, s33, v[6:7]
	s_waitcnt vmcnt(31)
	ds_write_b32 v118, v162
	s_waitcnt vmcnt(30)
	ds_write_b32 v130, v163
	s_waitcnt vmcnt(29)
	ds_write_b32 v132, v164
	s_waitcnt vmcnt(28)
	ds_write_b32 v134, v165
	s_waitcnt vmcnt(27)
	ds_write_b32 v136, v166
	s_waitcnt vmcnt(26)
	ds_write_b32 v138, v167
	s_waitcnt vmcnt(25)
	ds_write_b32 v140, v168
	s_waitcnt vmcnt(24)
	ds_write_b32 v142, v169
	s_waitcnt vmcnt(23)
	ds_write_b32 v144, v170
	s_waitcnt vmcnt(22)
	ds_write_b32 v146, v171
	s_waitcnt vmcnt(21)
	ds_write_b32 v148, v172
	s_waitcnt vmcnt(20)
	ds_write_b32 v150, v173
	s_waitcnt vmcnt(19)
	ds_write_b32 v152, v104
	s_waitcnt vmcnt(18)
	ds_write_b32 v154, v174
	s_waitcnt vmcnt(17)
	ds_write_b32 v156, v175
	s_waitcnt vmcnt(16)
	ds_write_b32 v158, v176
	s_waitcnt vmcnt(15)
	ds_write_b32 v18, v62
	s_waitcnt vmcnt(14)
	ds_write_b32 v30, v63
	s_waitcnt vmcnt(13)
	ds_write_b32 v32, v64
	s_waitcnt vmcnt(12)
	ds_write_b32 v34, v65
	s_waitcnt vmcnt(11)
	ds_write_b32 v36, v66
	s_waitcnt vmcnt(10)
	ds_write_b32 v38, v67
	s_waitcnt vmcnt(9)
	ds_write_b32 v40, v68
	s_waitcnt vmcnt(8)
	ds_write_b32 v42, v69
	s_waitcnt vmcnt(7)
	ds_write_b32 v44, v70
	s_waitcnt vmcnt(6)
	ds_write_b32 v46, v71
	s_waitcnt vmcnt(5)
	ds_write_b32 v48, v72
	s_waitcnt vmcnt(4)
	ds_write_b32 v50, v73
	s_waitcnt vmcnt(3)
	ds_write_b32 v52, v4
	s_waitcnt vmcnt(2)
	ds_write_b32 v54, v74
	s_waitcnt vmcnt(1)
	ds_write_b32 v56, v75
	s_waitcnt vmcnt(0)
	ds_write_b32 v58, v76
	s_waitcnt lgkmcnt(0)
	ds_read2_b32 v[16:17], v22 offset1:8
	ds_read2_b32 v[30:31], v22 offset0:33 offset1:41
	v_mul_hi_i32_i24_e32 v13, 0x1c0000, v12
	v_mul_i32_i24_e32 v12, 0x1c0000, v12
	ds_read2_b32 v[32:33], v22 offset0:66 offset1:74
	v_lshl_add_u64 v[12:13], s[8:9], 0, v[12:13]
	v_lshlrev_b32_e32 v4, 1, v14
	ds_read2_b32 v[34:35], v22 offset0:99 offset1:107
	v_lshl_add_u64 v[12:13], v[12:13], 0, v[4:5]
	s_waitcnt lgkmcnt(3)
	v_bfe_u32 v4, v16, 16, 1
	v_add_u32_e32 v3, 0x300, v11
	v_mov_b32_e32 v11, v5
	v_add3_u32 v4, v16, v4, s45
	s_waitcnt lgkmcnt(2)
	v_bfe_u32 v9, v30, 16, 1
	ds_read2_b32 v[36:37], v22 offset0:132 offset1:140
	v_lshl_add_u64 v[12:13], v[12:13], 0, v[10:11]
	v_lshrrev_b32_e32 v4, 16, v4
	v_add3_u32 v9, v30, v9, s45
	ds_read2_b32 v[38:39], v22 offset0:165 offset1:173
	v_lshl_add_u64 v[18:19], v[12:13], 0, s[22:23]
	v_and_or_b32 v12, v9, s46, v4
	s_waitcnt lgkmcnt(3)
	v_bfe_u32 v4, v32, 16, 1
	v_add3_u32 v4, v32, v4, s45
	s_waitcnt lgkmcnt(2)
	v_bfe_u32 v9, v34, 16, 1
	ds_read2_b32 v[40:41], v22 offset0:198 offset1:206
	v_lshrrev_b32_e32 v4, 16, v4
	v_add3_u32 v9, v34, v9, s45
	ds_read2_b32 v[42:43], v22 offset0:231 offset1:239
	v_and_or_b32 v13, v9, s46, v4
	s_waitcnt lgkmcnt(3)
	v_bfe_u32 v4, v36, 16, 1
	v_add3_u32 v4, v36, v4, s45
	s_waitcnt lgkmcnt(2)
	v_bfe_u32 v9, v38, 16, 1
	v_lshrrev_b32_e32 v4, 16, v4
	v_add3_u32 v9, v38, v9, s45
	v_and_or_b32 v14, v9, s46, v4
	s_waitcnt lgkmcnt(1)
	v_bfe_u32 v4, v40, 16, 1
	v_add3_u32 v4, v40, v4, s45
	s_waitcnt lgkmcnt(0)
	v_bfe_u32 v9, v42, 16, 1
	v_lshrrev_b32_e32 v4, 16, v4
	v_add3_u32 v9, v42, v9, s45
	v_and_or_b32 v15, v9, s46, v4
	v_or_b32_e32 v4, v3, v21
	v_lshlrev_b32_e32 v4, 10, v4
	v_lshl_add_u64 v[44:45], v[18:19], 0, v[4:5]
	v_bfe_u32 v4, v17, 16, 1
	v_add3_u32 v4, v17, v4, s45
	v_bfe_u32 v9, v31, 16, 1
	v_lshrrev_b32_e32 v4, 16, v4
	v_add3_u32 v9, v31, v9, s45
	global_store_dwordx4 v[44:45], v[12:15], off nt
	ds_read2_b32 v[16:17], v22 offset0:16 offset1:24
	v_readlane_b32 s66, v253, 1
	v_and_or_b32 v12, v9, s46, v4
	v_bfe_u32 v4, v33, 16, 1
	v_add3_u32 v4, v33, v4, s45
	v_bfe_u32 v9, v35, 16, 1
	v_lshrrev_b32_e32 v4, 16, v4
	v_add3_u32 v9, v35, v9, s45
	v_and_or_b32 v13, v9, s46, v4
	v_bfe_u32 v4, v37, 16, 1
	v_add3_u32 v4, v37, v4, s45
	v_bfe_u32 v9, v39, 16, 1
	v_lshrrev_b32_e32 v4, 16, v4
	v_add3_u32 v9, v39, v9, s45
	v_and_or_b32 v14, v9, s46, v4
	v_bfe_u32 v4, v41, 16, 1
	v_add3_u32 v4, v41, v4, s45
	v_bfe_u32 v9, v43, 16, 1
	v_lshrrev_b32_e32 v4, 16, v4
	v_add3_u32 v9, v43, v9, s45
	v_and_or_b32 v15, v9, s46, v4
	v_or_b32_e32 v4, v3, v23
	v_lshlrev_b32_e32 v4, 10, v4
	v_lshl_add_u64 v[30:31], v[18:19], 0, v[4:5]
	global_store_dwordx4 v[30:31], v[12:15], off nt
	ds_read2_b32 v[30:31], v22 offset0:49 offset1:57
	ds_read2_b32 v[32:33], v22 offset0:82 offset1:90
	ds_read2_b32 v[34:35], v22 offset0:115 offset1:123
	s_waitcnt lgkmcnt(3)
	v_bfe_u32 v4, v16, 16, 1
	v_add3_u32 v4, v16, v4, s45
	s_waitcnt lgkmcnt(2)
	v_bfe_u32 v9, v30, 16, 1
	ds_read2_b32 v[36:37], v22 offset0:148 offset1:156
	v_lshrrev_b32_e32 v4, 16, v4
	v_add3_u32 v9, v30, v9, s45
	ds_read2_b32 v[38:39], v22 offset0:181 offset1:189
	v_and_or_b32 v12, v9, s46, v4
	s_waitcnt lgkmcnt(3)
	v_bfe_u32 v4, v32, 16, 1
	v_add3_u32 v4, v32, v4, s45
	s_waitcnt lgkmcnt(2)
	v_bfe_u32 v9, v34, 16, 1
	ds_read2_b32 v[40:41], v22 offset0:214 offset1:222
	v_lshrrev_b32_e32 v4, 16, v4
	v_add3_u32 v9, v34, v9, s45
	ds_read2_b32 v[42:43], v22 offset0:247 offset1:255
	v_and_or_b32 v13, v9, s46, v4
	s_waitcnt lgkmcnt(3)
	v_bfe_u32 v4, v36, 16, 1
	v_add3_u32 v4, v36, v4, s45
	s_waitcnt lgkmcnt(2)
	v_bfe_u32 v9, v38, 16, 1
	v_lshrrev_b32_e32 v4, 16, v4
	v_add3_u32 v9, v38, v9, s45
	v_and_or_b32 v14, v9, s46, v4
	s_waitcnt lgkmcnt(1)
	v_bfe_u32 v4, v40, 16, 1
	v_add3_u32 v4, v40, v4, s45
	s_waitcnt lgkmcnt(0)
	v_bfe_u32 v9, v42, 16, 1
	v_lshrrev_b32_e32 v4, 16, v4
	v_add3_u32 v9, v42, v9, s45
	v_and_or_b32 v15, v9, s46, v4
	v_or_b32_e32 v4, v3, v24
	v_lshlrev_b32_e32 v4, 10, v4
	v_lshl_add_u64 v[44:45], v[18:19], 0, v[4:5]
	v_bfe_u32 v4, v17, 16, 1
	v_add3_u32 v4, v17, v4, s45
	v_bfe_u32 v9, v31, 16, 1
	v_lshrrev_b32_e32 v4, 16, v4
	v_add3_u32 v9, v31, v9, s45
	global_store_dwordx4 v[44:45], v[12:15], off nt
	v_or_b32_e32 v3, v3, v25
	s_nop 0
	v_and_or_b32 v12, v9, s46, v4
	v_bfe_u32 v4, v33, 16, 1
	v_add3_u32 v4, v33, v4, s45
	v_bfe_u32 v9, v35, 16, 1
	v_lshrrev_b32_e32 v4, 16, v4
	v_add3_u32 v9, v35, v9, s45
	v_and_or_b32 v13, v9, s46, v4
	v_bfe_u32 v4, v37, 16, 1
	v_add3_u32 v4, v37, v4, s45
	v_bfe_u32 v9, v39, 16, 1
	v_lshrrev_b32_e32 v4, 16, v4
	v_add3_u32 v9, v39, v9, s45
	v_and_or_b32 v14, v9, s46, v4
	v_bfe_u32 v4, v41, 16, 1
	v_add3_u32 v4, v41, v4, s45
	v_bfe_u32 v9, v43, 16, 1
	v_lshrrev_b32_e32 v4, 16, v4
	v_add3_u32 v9, v43, v9, s45
	v_and_or_b32 v15, v9, s46, v4
	v_lshlrev_b32_e32 v4, 10, v3
	v_lshl_add_u64 v[16:17], v[18:19], 0, v[4:5]
	global_store_dwordx4 v[16:17], v[12:15], off nt
	s_waitcnt lgkmcnt(0)
.LBB0_115:
	s_andn2_saveexec_b64 s[36:37], s[36:37]
	s_cbranch_execz .LBB0_119
	v_subrev_u16_e32 v3, 64, v3
	s_load_dwordx2 s[58:59], s[6:7], 0x58
	v_mul_lo_u16_sdwa v4, v3, s47 dst_sel:DWORD dst_unused:UNUSED_PAD src0_sel:BYTE_0 src1_sel:DWORD
	v_lshrrev_b16_e32 v4, 12, v4
	v_mul_lo_u16_e32 v9, 24, v4
	v_sub_u16_e32 v3, v3, v9
	v_mul_hi_i32_i24_e32 v15, 0x120000, v12
	v_mul_i32_i24_e32 v14, 0x120000, v12
	s_waitcnt lgkmcnt(0)
	v_lshl_add_u64 v[16:17], s[58:59], 0, v[14:15]
	v_lshlrev_b32_e32 v14, 6, v4
	v_lshlrev_b32_sdwa v4, v27, v3 dst_sel:DWORD dst_unused:UNUSED_PAD src0_sel:DWORD src1_sel:BYTE_0
	v_lshl_add_u64 v[16:17], v[16:17], 0, v[4:5]
	v_mov_b32_e32 v9, v5
	v_lshlrev_b32_sdwa v13, v26, v3 dst_sel:DWORD dst_unused:UNUSED_PAD src0_sel:DWORD src1_sel:BYTE_0
	v_lshl_add_u64 v[16:17], v[16:17], 0, v[8:9]
	v_mov_b32_e32 v3, v14
	s_mov_b32 s58, 1
	s_mov_b32 s59, 0
	s_mov_b32 s60, 32
	s_lshl_b32 s61, s58, 1
	s_lshl_b32 s62, s59, 1
	v_or_b32_e32 v104, s61, v1
	v_or_b32_e32 v109, s62, v2
	s_add_i32 s63, s61, 4
	s_add_i32 s64, s62, 4
	s_add_i32 s65, s61, 8
	s_add_i32 s66, s62, 8
	s_add_i32 s67, s61, 12
	s_add_i32 s68, s62, 12
	s_add_i32 s69, s61, 16
	s_add_i32 s70, s62, 16
	s_add_i32 s71, s61, 20
	s_add_i32 s72, s62, 20
	s_add_i32 s73, s61, 24
	s_add_i32 s74, s62, 24
	s_add_i32 s61, s61, 28
	s_add_i32 s62, s62, 28
	v_add_u32_e32 v111, v104, v3
	v_add_u32_e32 v115, v109, v14
	v_or_b32_e32 v129, s63, v1
	v_or_b32_e32 v160, s64, v2
	v_or_b32_e32 v161, s65, v1
	v_or_b32_e32 v162, s66, v2
	v_or_b32_e32 v163, s67, v1
	v_or_b32_e32 v164, s68, v2
	v_or_b32_e32 v165, s69, v1
	v_or_b32_e32 v166, s70, v2
	v_or_b32_e32 v167, s71, v1
	v_or_b32_e32 v168, s72, v2
	v_or_b32_e32 v169, s73, v1
	v_or_b32_e32 v170, s74, v2
	v_or_b32_e32 v171, s61, v1
	v_or_b32_e32 v172, s62, v2
	v_mad_u64_u32 v[118:119], s[62:63], v115, s48, v[16:17]
	v_mad_u64_u32 v[130:131], s[62:63], v111, s48, v[16:17]
	v_add_u32_e32 v111, v129, v3
	v_add_u32_e32 v115, v160, v14
	v_add_u32_e32 v138, v161, v3
	v_add_u32_e32 v136, v162, v14
	v_add_u32_e32 v142, v163, v3
	v_add_u32_e32 v140, v164, v14
	v_add_u32_e32 v146, v165, v3
	v_add_u32_e32 v144, v166, v14
	v_add_u32_e32 v150, v167, v3
	v_add_u32_e32 v148, v168, v14
	v_add_u32_e32 v154, v169, v3
	v_add_u32_e32 v152, v170, v14
	v_add_u32_e32 v158, v171, v3
	v_add_u32_e32 v156, v172, v14
	v_mad_u64_u32 v[132:133], s[62:63], v115, s48, v[16:17]
	v_mad_u64_u32 v[134:135], s[62:63], v111, s48, v[16:17]
	v_mad_u64_u32 v[136:137], s[62:63], v136, s48, v[16:17]
	v_mad_u64_u32 v[138:139], s[62:63], v138, s48, v[16:17]
	v_mad_u64_u32 v[140:141], s[62:63], v140, s48, v[16:17]
	v_mad_u64_u32 v[142:143], s[62:63], v142, s48, v[16:17]
	v_mad_u64_u32 v[144:145], s[62:63], v144, s48, v[16:17]
	v_mad_u64_u32 v[146:147], s[62:63], v146, s48, v[16:17]
	v_mad_u64_u32 v[148:149], s[62:63], v148, s48, v[16:17]
	v_mad_u64_u32 v[150:151], s[62:63], v150, s48, v[16:17]
	v_mad_u64_u32 v[152:153], s[62:63], v152, s48, v[16:17]
	v_mad_u64_u32 v[154:155], s[62:63], v154, s48, v[16:17]
	v_mad_u64_u32 v[156:157], s[62:63], v156, s48, v[16:17]
	v_mad_u64_u32 v[158:159], s[62:63], v158, s48, v[16:17]
	global_load_dword v111, v[118:119], off nt
	global_load_dword v115, v[130:131], off nt
	global_load_dword v173, v[132:133], off nt
	global_load_dword v174, v[134:135], off nt
	global_load_dword v175, v[136:137], off nt
	global_load_dword v176, v[138:139], off nt
	global_load_dword v177, v[140:141], off nt
	global_load_dword v178, v[142:143], off nt
	global_load_dword v179, v[144:145], off nt
	global_load_dword v180, v[146:147], off nt
	global_load_dword v181, v[148:149], off nt
	global_load_dword v182, v[150:151], off nt
	global_load_dword v183, v[152:153], off nt
	global_load_dword v184, v[154:155], off nt
	global_load_dword v185, v[156:157], off nt
	global_load_dword v186, v[158:159], off nt
	s_add_i32 s59, s59, 16
	s_add_i32 s58, s58, 16
	s_add_i32 s60, s60, -16
	v_mad_u64_u32 v[118:119], s[62:63], v109, s33, v[6:7]
	v_mad_u64_u32 v[130:131], s[62:63], v104, s33, v[6:7]
	v_mad_u64_u32 v[132:133], s[62:63], v160, s33, v[6:7]
	v_mad_u64_u32 v[134:135], s[62:63], v129, s33, v[6:7]
	v_mad_u64_u32 v[136:137], s[62:63], v162, s33, v[6:7]
	v_mad_u64_u32 v[138:139], s[62:63], v161, s33, v[6:7]
	v_mad_u64_u32 v[140:141], s[62:63], v164, s33, v[6:7]
	v_mad_u64_u32 v[142:143], s[62:63], v163, s33, v[6:7]
	v_mad_u64_u32 v[144:145], s[62:63], v166, s33, v[6:7]
	v_mad_u64_u32 v[146:147], s[62:63], v165, s33, v[6:7]
	v_mad_u64_u32 v[148:149], s[62:63], v168, s33, v[6:7]
	v_mad_u64_u32 v[150:151], s[62:63], v167, s33, v[6:7]
	v_mad_u64_u32 v[152:153], s[62:63], v170, s33, v[6:7]
	v_mad_u64_u32 v[154:155], s[62:63], v169, s33, v[6:7]
	v_mad_u64_u32 v[156:157], s[62:63], v172, s33, v[6:7]
	v_mad_u64_u32 v[158:159], s[62:63], v171, s33, v[6:7]
	s_lshl_b32 s61, s58, 1
	s_lshl_b32 s62, s59, 1
	v_or_b32_e32 v4, s61, v1
	v_or_b32_e32 v9, s62, v2
	s_add_i32 s63, s61, 4
	s_add_i32 s64, s62, 4
	s_add_i32 s65, s61, 8
	s_add_i32 s66, s62, 8
	s_add_i32 s67, s61, 12
	s_add_i32 s68, s62, 12
	s_add_i32 s69, s61, 16
	s_add_i32 s70, s62, 16
	s_add_i32 s71, s61, 20
	s_add_i32 s72, s62, 20
	s_add_i32 s73, s61, 24
	s_add_i32 s74, s62, 24
	s_add_i32 s61, s61, 28
	s_add_i32 s62, s62, 28
	v_add_u32_e32 v11, v4, v3
	v_add_u32_e32 v15, v9, v14
	v_or_b32_e32 v29, s63, v1
	v_or_b32_e32 v60, s64, v2
	v_or_b32_e32 v61, s65, v1
	v_or_b32_e32 v62, s66, v2
	v_or_b32_e32 v63, s67, v1
	v_or_b32_e32 v64, s68, v2
	v_or_b32_e32 v65, s69, v1
	v_or_b32_e32 v66, s70, v2
	v_or_b32_e32 v67, s71, v1
	v_or_b32_e32 v68, s72, v2
	v_or_b32_e32 v69, s73, v1
	v_or_b32_e32 v70, s74, v2
	v_or_b32_e32 v71, s61, v1
	v_or_b32_e32 v72, s62, v2
	v_mad_u64_u32 v[18:19], s[62:63], v15, s48, v[16:17]
	v_mad_u64_u32 v[30:31], s[62:63], v11, s48, v[16:17]
	v_add_u32_e32 v11, v29, v3
	v_add_u32_e32 v15, v60, v14
	v_add_u32_e32 v38, v61, v3
	v_add_u32_e32 v36, v62, v14
	v_add_u32_e32 v42, v63, v3
	v_add_u32_e32 v40, v64, v14
	v_add_u32_e32 v46, v65, v3
	v_add_u32_e32 v44, v66, v14
	v_add_u32_e32 v50, v67, v3
	v_add_u32_e32 v48, v68, v14
	v_add_u32_e32 v54, v69, v3
	v_add_u32_e32 v52, v70, v14
	v_add_u32_e32 v58, v71, v3
	v_add_u32_e32 v56, v72, v14
	v_mad_u64_u32 v[32:33], s[62:63], v15, s48, v[16:17]
	v_mad_u64_u32 v[34:35], s[62:63], v11, s48, v[16:17]
	v_mad_u64_u32 v[36:37], s[62:63], v36, s48, v[16:17]
	v_mad_u64_u32 v[38:39], s[62:63], v38, s48, v[16:17]
	v_mad_u64_u32 v[40:41], s[62:63], v40, s48, v[16:17]
	v_mad_u64_u32 v[42:43], s[62:63], v42, s48, v[16:17]
	v_mad_u64_u32 v[44:45], s[62:63], v44, s48, v[16:17]
	v_mad_u64_u32 v[46:47], s[62:63], v46, s48, v[16:17]
	v_mad_u64_u32 v[48:49], s[62:63], v48, s48, v[16:17]
	v_mad_u64_u32 v[50:51], s[62:63], v50, s48, v[16:17]
	v_mad_u64_u32 v[52:53], s[62:63], v52, s48, v[16:17]
	v_mad_u64_u32 v[54:55], s[62:63], v54, s48, v[16:17]
	v_mad_u64_u32 v[56:57], s[62:63], v56, s48, v[16:17]
	v_mad_u64_u32 v[58:59], s[62:63], v58, s48, v[16:17]
	global_load_dword v11, v[18:19], off nt
	global_load_dword v15, v[30:31], off nt
	global_load_dword v73, v[32:33], off nt
	global_load_dword v74, v[34:35], off nt
	global_load_dword v75, v[36:37], off nt
	global_load_dword v76, v[38:39], off nt
	global_load_dword v77, v[40:41], off nt
	global_load_dword v78, v[42:43], off nt
	global_load_dword v79, v[44:45], off nt
	global_load_dword v80, v[46:47], off nt
	global_load_dword v81, v[48:49], off nt
	global_load_dword v82, v[50:51], off nt
	global_load_dword v83, v[52:53], off nt
	global_load_dword v84, v[54:55], off nt
	global_load_dword v85, v[56:57], off nt
	global_load_dword v86, v[58:59], off nt
	s_add_i32 s59, s59, 16
	s_add_i32 s58, s58, 16
	s_add_i32 s60, s60, -16
	v_mad_u64_u32 v[18:19], s[62:63], v9, s33, v[6:7]
	v_mad_u64_u32 v[30:31], s[62:63], v4, s33, v[6:7]
	v_mad_u64_u32 v[32:33], s[62:63], v60, s33, v[6:7]
	v_mad_u64_u32 v[34:35], s[62:63], v29, s33, v[6:7]
	v_mad_u64_u32 v[36:37], s[62:63], v62, s33, v[6:7]
	v_mad_u64_u32 v[38:39], s[62:63], v61, s33, v[6:7]
	v_mad_u64_u32 v[40:41], s[62:63], v64, s33, v[6:7]
	v_mad_u64_u32 v[42:43], s[62:63], v63, s33, v[6:7]
	v_mad_u64_u32 v[44:45], s[62:63], v66, s33, v[6:7]
	v_mad_u64_u32 v[46:47], s[62:63], v65, s33, v[6:7]
	v_mad_u64_u32 v[48:49], s[62:63], v68, s33, v[6:7]
	v_mad_u64_u32 v[50:51], s[62:63], v67, s33, v[6:7]
	v_mad_u64_u32 v[52:53], s[62:63], v70, s33, v[6:7]
	v_mad_u64_u32 v[54:55], s[62:63], v69, s33, v[6:7]
	v_mad_u64_u32 v[56:57], s[62:63], v72, s33, v[6:7]
	v_mad_u64_u32 v[58:59], s[62:63], v71, s33, v[6:7]
	s_waitcnt vmcnt(31)
	ds_write_b32 v118, v111
	s_waitcnt vmcnt(30)
	ds_write_b32 v130, v115
	s_waitcnt vmcnt(29)
	ds_write_b32 v132, v173
	s_waitcnt vmcnt(28)
	ds_write_b32 v134, v174
	s_waitcnt vmcnt(27)
	ds_write_b32 v136, v175
	s_waitcnt vmcnt(26)
	ds_write_b32 v138, v176
	s_waitcnt vmcnt(25)
	ds_write_b32 v140, v177
	s_waitcnt vmcnt(24)
	ds_write_b32 v142, v178
	s_waitcnt vmcnt(23)
	ds_write_b32 v144, v179
	s_waitcnt vmcnt(22)
	ds_write_b32 v146, v180
	s_waitcnt vmcnt(21)
	ds_write_b32 v148, v181
	s_waitcnt vmcnt(20)
	ds_write_b32 v150, v182
	s_waitcnt vmcnt(19)
	ds_write_b32 v152, v183
	s_waitcnt vmcnt(18)
	ds_write_b32 v154, v184
	s_waitcnt vmcnt(17)
	ds_write_b32 v156, v185
	s_waitcnt vmcnt(16)
	ds_write_b32 v158, v186
	s_waitcnt vmcnt(15)
	ds_write_b32 v18, v11
	s_waitcnt vmcnt(14)
	ds_write_b32 v30, v15
	s_waitcnt vmcnt(13)
	ds_write_b32 v32, v73
	s_waitcnt vmcnt(12)
	ds_write_b32 v34, v74
	s_waitcnt vmcnt(11)
	ds_write_b32 v36, v75
	s_waitcnt vmcnt(10)
	ds_write_b32 v38, v76
	s_waitcnt vmcnt(9)
	ds_write_b32 v40, v77
	s_waitcnt vmcnt(8)
	ds_write_b32 v42, v78
	s_waitcnt vmcnt(7)
	ds_write_b32 v44, v79
	s_waitcnt vmcnt(6)
	ds_write_b32 v46, v80
	s_waitcnt vmcnt(5)
	ds_write_b32 v48, v81
	s_waitcnt vmcnt(4)
	ds_write_b32 v50, v82
	s_waitcnt vmcnt(3)
	ds_write_b32 v52, v83
	s_waitcnt vmcnt(2)
	ds_write_b32 v54, v84
	s_waitcnt vmcnt(1)
	ds_write_b32 v56, v85
	s_waitcnt vmcnt(0)
	ds_write_b32 v58, v86
	s_waitcnt lgkmcnt(0)
	ds_read2_b32 v[18:19], v22 offset1:8
	ds_read2_b32 v[32:33], v22 offset0:33 offset1:41
	ds_read2_b32 v[34:35], v22 offset0:66 offset1:74
	v_mul_hi_i32_i24_e32 v17, 0x1c0000, v12
	v_mul_i32_i24_e32 v16, 0x1c0000, v12
	ds_read2_b32 v[36:37], v22 offset0:99 offset1:107
	v_lshl_add_u64 v[16:17], s[10:11], 0, v[16:17]
	v_lshlrev_b32_e32 v4, 1, v14
	s_waitcnt lgkmcnt(3)
	v_bfe_u32 v3, v18, 16, 1
	v_lshl_add_u64 v[14:15], v[16:17], 0, v[4:5]
	v_add3_u32 v3, v18, v3, s45
	s_waitcnt lgkmcnt(2)
	v_bfe_u32 v4, v32, 16, 1
	ds_read2_b32 v[38:39], v22 offset0:132 offset1:140
	v_mov_b32_e32 v11, v5
	v_lshrrev_b32_e32 v3, 16, v3
	v_add3_u32 v4, v32, v4, s45
	ds_read2_b32 v[40:41], v22 offset0:165 offset1:173
	v_lshl_add_u64 v[30:31], v[14:15], 0, v[10:11]
	v_and_or_b32 v14, v4, s46, v3
	s_waitcnt lgkmcnt(3)
	v_bfe_u32 v3, v34, 16, 1
	v_add3_u32 v3, v34, v3, s45
	s_waitcnt lgkmcnt(2)
	v_bfe_u32 v4, v36, 16, 1
	ds_read2_b32 v[42:43], v22 offset0:198 offset1:206
	v_lshrrev_b32_e32 v3, 16, v3
	v_add3_u32 v4, v36, v4, s45
	ds_read2_b32 v[44:45], v22 offset0:231 offset1:239
	v_and_or_b32 v15, v4, s46, v3
	s_waitcnt lgkmcnt(3)
	v_bfe_u32 v3, v38, 16, 1
	v_add3_u32 v3, v38, v3, s45
	s_waitcnt lgkmcnt(2)
	v_bfe_u32 v4, v40, 16, 1
	v_lshrrev_b32_e32 v3, 16, v3
	v_add3_u32 v4, v40, v4, s45
	v_and_or_b32 v16, v4, s46, v3
	s_waitcnt lgkmcnt(1)
	v_bfe_u32 v3, v42, 16, 1
	v_add3_u32 v3, v42, v3, s45
	s_waitcnt lgkmcnt(0)
	v_bfe_u32 v4, v44, 16, 1
	v_lshrrev_b32_e32 v3, 16, v3
	v_add3_u32 v4, v44, v4, s45
	v_and_or_b32 v17, v4, s46, v3
	v_or_b32_e32 v3, v13, v21
	v_lshlrev_b32_e32 v4, 10, v3
	v_bfe_u32 v3, v19, 16, 1
	v_lshl_add_u64 v[46:47], v[30:31], 0, v[4:5]
	v_add3_u32 v3, v19, v3, s45
	v_bfe_u32 v4, v33, 16, 1
	v_lshrrev_b32_e32 v3, 16, v3
	v_add3_u32 v4, v33, v4, s45
	global_store_dwordx4 v[46:47], v[14:17], off nt
	ds_read2_b32 v[18:19], v22 offset0:16 offset1:24
	v_readlane_b32 s66, v253, 1
	v_and_or_b32 v14, v4, s46, v3
	v_bfe_u32 v3, v35, 16, 1
	v_add3_u32 v3, v35, v3, s45
	v_bfe_u32 v4, v37, 16, 1
	v_lshrrev_b32_e32 v3, 16, v3
	v_add3_u32 v4, v37, v4, s45
	v_and_or_b32 v15, v4, s46, v3
	v_bfe_u32 v3, v39, 16, 1
	v_add3_u32 v3, v39, v3, s45
	v_bfe_u32 v4, v41, 16, 1
	v_lshrrev_b32_e32 v3, 16, v3
	v_add3_u32 v4, v41, v4, s45
	v_and_or_b32 v16, v4, s46, v3
	v_bfe_u32 v3, v43, 16, 1
	v_add3_u32 v3, v43, v3, s45
	v_bfe_u32 v4, v45, 16, 1
	v_lshrrev_b32_e32 v3, 16, v3
	v_add3_u32 v4, v45, v4, s45
	v_and_or_b32 v17, v4, s46, v3
	v_or_b32_e32 v3, v13, v23
	v_lshlrev_b32_e32 v4, 10, v3
	v_lshl_add_u64 v[32:33], v[30:31], 0, v[4:5]
	global_store_dwordx4 v[32:33], v[14:17], off nt
	ds_read2_b32 v[32:33], v22 offset0:49 offset1:57
	ds_read2_b32 v[34:35], v22 offset0:82 offset1:90
	ds_read2_b32 v[36:37], v22 offset0:115 offset1:123
	s_waitcnt lgkmcnt(3)
	v_bfe_u32 v3, v18, 16, 1
	v_add3_u32 v3, v18, v3, s45
	s_waitcnt lgkmcnt(2)
	v_bfe_u32 v4, v32, 16, 1
	ds_read2_b32 v[38:39], v22 offset0:148 offset1:156
	v_lshrrev_b32_e32 v3, 16, v3
	v_add3_u32 v4, v32, v4, s45
	ds_read2_b32 v[40:41], v22 offset0:181 offset1:189
	v_and_or_b32 v14, v4, s46, v3
	s_waitcnt lgkmcnt(3)
	v_bfe_u32 v3, v34, 16, 1
	v_add3_u32 v3, v34, v3, s45
	s_waitcnt lgkmcnt(2)
	v_bfe_u32 v4, v36, 16, 1
	ds_read2_b32 v[42:43], v22 offset0:214 offset1:222
	v_lshrrev_b32_e32 v3, 16, v3
	v_add3_u32 v4, v36, v4, s45
	ds_read2_b32 v[44:45], v22 offset0:247 offset1:255
	v_and_or_b32 v15, v4, s46, v3
	s_waitcnt lgkmcnt(3)
	v_bfe_u32 v3, v38, 16, 1
	v_add3_u32 v3, v38, v3, s45
	s_waitcnt lgkmcnt(2)
	v_bfe_u32 v4, v40, 16, 1
	v_lshrrev_b32_e32 v3, 16, v3
	v_add3_u32 v4, v40, v4, s45
	v_and_or_b32 v16, v4, s46, v3
	s_waitcnt lgkmcnt(1)
	v_bfe_u32 v3, v42, 16, 1
	v_add3_u32 v3, v42, v3, s45
	s_waitcnt lgkmcnt(0)
	v_bfe_u32 v4, v44, 16, 1
	v_lshrrev_b32_e32 v3, 16, v3
	v_add3_u32 v4, v44, v4, s45
	v_and_or_b32 v17, v4, s46, v3
	v_or_b32_e32 v3, v13, v24
	v_lshlrev_b32_e32 v4, 10, v3
	v_bfe_u32 v3, v19, 16, 1
	v_lshl_add_u64 v[46:47], v[30:31], 0, v[4:5]
	v_add3_u32 v3, v19, v3, s45
	v_bfe_u32 v4, v33, 16, 1
	v_lshrrev_b32_e32 v3, 16, v3
	v_add3_u32 v4, v33, v4, s45
	global_store_dwordx4 v[46:47], v[14:17], off nt
	s_nop 1
	v_and_or_b32 v14, v4, s46, v3
	v_bfe_u32 v3, v35, 16, 1
	v_add3_u32 v3, v35, v3, s45
	v_bfe_u32 v4, v37, 16, 1
	v_lshrrev_b32_e32 v3, 16, v3
	v_add3_u32 v4, v37, v4, s45
	v_and_or_b32 v15, v4, s46, v3
	v_bfe_u32 v3, v39, 16, 1
	v_add3_u32 v3, v39, v3, s45
	v_bfe_u32 v4, v41, 16, 1
	v_lshrrev_b32_e32 v3, 16, v3
	v_add3_u32 v4, v41, v4, s45
	v_and_or_b32 v16, v4, s46, v3
	v_bfe_u32 v3, v43, 16, 1
	v_add3_u32 v3, v43, v3, s45
	v_bfe_u32 v4, v45, 16, 1
	v_lshrrev_b32_e32 v3, 16, v3
	v_add3_u32 v4, v45, v4, s45
	v_and_or_b32 v17, v4, s46, v3
	v_or_b32_e32 v3, v13, v25
	v_lshlrev_b32_e32 v4, 10, v3
	v_lshl_add_u64 v[12:13], v[30:31], 0, v[4:5]
	global_store_dwordx4 v[12:13], v[14:17], off nt
	s_waitcnt lgkmcnt(0)

.LBB0_120:
	s_andn2_saveexec_b64 s[34:35], s[34:35]
	s_cbranch_execz .LBB0_124
	s_load_dwordx2 s[36:37], s[6:7], 0xb0
	v_and_b32_e32 v4, 0x7fc0, v3
	v_lshlrev_b32_e32 v3, 5, v3
	v_and_b32_e32 v13, 0x7e0, v3
	v_add_u32_e32 v14, 0xffffbbc0, v4
	s_waitcnt lgkmcnt(0)
	v_mov_b64_e32 v[16:17], s[36:37]
	v_mad_i64_i32 v[16:17], s[36:37], v12, s49, v[16:17]
	v_lshlrev_b32_e32 v4, 2, v13
	v_lshl_add_u64 v[16:17], v[16:17], 0, v[4:5]
	v_mov_b32_e32 v9, v5
	v_lshl_add_u64 v[16:17], v[16:17], 0, v[8:9]
	v_mov_b32_e32 v3, v14
	s_mov_b32 s36, 1
	s_mov_b32 s37, 0
	s_mov_b32 s58, 32
	s_lshl_b32 s59, s36, 1
	s_lshl_b32 s60, s37, 1
	v_or_b32_e32 v104, s59, v1
	v_or_b32_e32 v109, s60, v2
	s_add_i32 s61, s59, 4
	s_add_i32 s62, s60, 4
	s_add_i32 s63, s59, 8
	s_add_i32 s64, s60, 8
	s_add_i32 s65, s59, 12
	s_add_i32 s66, s60, 12
	s_add_i32 s67, s59, 16
	s_add_i32 s68, s60, 16
	s_add_i32 s69, s59, 20
	s_add_i32 s70, s60, 20
	s_add_i32 s71, s59, 24
	s_add_i32 s72, s60, 24
	s_add_i32 s59, s59, 28
	s_add_i32 s60, s60, 28
	v_add_u32_e32 v130, v109, v14
	v_or_b32_e32 v111, s61, v1
	v_or_b32_e32 v115, s62, v2
	v_or_b32_e32 v129, s63, v1
	v_or_b32_e32 v160, s64, v2
	v_or_b32_e32 v161, s65, v1
	v_or_b32_e32 v162, s66, v2
	v_or_b32_e32 v163, s67, v1
	v_or_b32_e32 v164, s68, v2
	v_or_b32_e32 v165, s69, v1
	v_or_b32_e32 v166, s70, v2
	v_or_b32_e32 v167, s71, v1
	v_or_b32_e32 v168, s72, v2
	v_or_b32_e32 v169, s59, v1
	v_or_b32_e32 v170, s60, v2
	v_add_u32_e32 v118, v104, v3
	v_ashrrev_i32_e32 v131, 31, v130
	v_add_u32_e32 v132, v111, v3
	v_add_u32_e32 v134, v115, v14
	v_add_u32_e32 v136, v129, v3
	v_add_u32_e32 v138, v160, v14
	v_add_u32_e32 v140, v161, v3
	v_add_u32_e32 v142, v162, v14
	v_add_u32_e32 v144, v163, v3
	v_add_u32_e32 v146, v164, v14
	v_add_u32_e32 v148, v165, v3
	v_add_u32_e32 v150, v166, v14
	v_add_u32_e32 v152, v167, v3
	v_add_u32_e32 v154, v168, v14
	v_add_u32_e32 v156, v169, v3
	v_add_u32_e32 v158, v170, v14
	v_ashrrev_i32_e32 v119, 31, v118
	v_lshlrev_b64 v[130:131], 13, v[130:131]
	v_ashrrev_i32_e32 v135, 31, v134
	v_ashrrev_i32_e32 v133, 31, v132
	v_ashrrev_i32_e32 v139, 31, v138
	v_ashrrev_i32_e32 v137, 31, v136
	v_ashrrev_i32_e32 v143, 31, v142
	v_ashrrev_i32_e32 v141, 31, v140
	v_ashrrev_i32_e32 v147, 31, v146
	v_ashrrev_i32_e32 v145, 31, v144
	v_ashrrev_i32_e32 v151, 31, v150
	v_ashrrev_i32_e32 v149, 31, v148
	v_ashrrev_i32_e32 v155, 31, v154
	v_ashrrev_i32_e32 v153, 31, v152
	v_ashrrev_i32_e32 v159, 31, v158
	v_ashrrev_i32_e32 v157, 31, v156
	v_lshlrev_b64 v[118:119], 13, v[118:119]
	v_lshl_add_u64 v[130:131], v[16:17], 0, v[130:131]
	v_lshlrev_b64 v[132:133], 13, v[132:133]
	v_lshlrev_b64 v[134:135], 13, v[134:135]
	v_lshlrev_b64 v[136:137], 13, v[136:137]
	v_lshlrev_b64 v[138:139], 13, v[138:139]
	v_lshlrev_b64 v[140:141], 13, v[140:141]
	v_lshlrev_b64 v[142:143], 13, v[142:143]
	v_lshlrev_b64 v[144:145], 13, v[144:145]
	v_lshlrev_b64 v[146:147], 13, v[146:147]
	v_lshlrev_b64 v[148:149], 13, v[148:149]
	v_lshlrev_b64 v[150:151], 13, v[150:151]
	v_lshlrev_b64 v[152:153], 13, v[152:153]
	v_lshlrev_b64 v[154:155], 13, v[154:155]
	v_lshlrev_b64 v[156:157], 13, v[156:157]
	v_lshlrev_b64 v[158:159], 13, v[158:159]
	v_lshl_add_u64 v[118:119], v[16:17], 0, v[118:119]
	v_lshl_add_u64 v[134:135], v[16:17], 0, v[134:135]
	v_lshl_add_u64 v[132:133], v[16:17], 0, v[132:133]
	v_lshl_add_u64 v[138:139], v[16:17], 0, v[138:139]
	v_lshl_add_u64 v[136:137], v[16:17], 0, v[136:137]
	v_lshl_add_u64 v[142:143], v[16:17], 0, v[142:143]
	v_lshl_add_u64 v[140:141], v[16:17], 0, v[140:141]
	v_lshl_add_u64 v[146:147], v[16:17], 0, v[146:147]
	v_lshl_add_u64 v[144:145], v[16:17], 0, v[144:145]
	v_lshl_add_u64 v[150:151], v[16:17], 0, v[150:151]
	v_lshl_add_u64 v[148:149], v[16:17], 0, v[148:149]
	v_lshl_add_u64 v[154:155], v[16:17], 0, v[154:155]
	v_lshl_add_u64 v[152:153], v[16:17], 0, v[152:153]
	v_lshl_add_u64 v[158:159], v[16:17], 0, v[158:159]
	v_lshl_add_u64 v[156:157], v[16:17], 0, v[156:157]
	global_load_dword v171, v[130:131], off nt
	global_load_dword v172, v[118:119], off nt
	global_load_dword v173, v[134:135], off nt
	global_load_dword v174, v[132:133], off nt
	global_load_dword v175, v[138:139], off nt
	global_load_dword v176, v[136:137], off nt
	global_load_dword v177, v[142:143], off nt
	global_load_dword v178, v[140:141], off nt
	global_load_dword v179, v[146:147], off nt
	global_load_dword v180, v[144:145], off nt
	global_load_dword v181, v[150:151], off nt
	global_load_dword v182, v[148:149], off nt
	global_load_dword v183, v[154:155], off nt
	global_load_dword v184, v[152:153], off nt
	global_load_dword v185, v[158:159], off nt
	global_load_dword v186, v[156:157], off nt
	s_add_i32 s37, s37, 16
	s_add_i32 s36, s36, 16
	s_add_i32 s58, s58, -16
	v_mad_u64_u32 v[118:119], s[60:61], v109, s33, v[6:7]
	v_mad_u64_u32 v[130:131], s[60:61], v104, s33, v[6:7]
	v_mad_u64_u32 v[132:133], s[60:61], v115, s33, v[6:7]
	v_mad_u64_u32 v[134:135], s[60:61], v111, s33, v[6:7]
	v_mad_u64_u32 v[136:137], s[60:61], v160, s33, v[6:7]
	v_mad_u64_u32 v[138:139], s[60:61], v129, s33, v[6:7]
	v_mad_u64_u32 v[140:141], s[60:61], v162, s33, v[6:7]
	v_mad_u64_u32 v[142:143], s[60:61], v161, s33, v[6:7]
	v_mad_u64_u32 v[144:145], s[60:61], v164, s33, v[6:7]
	v_mad_u64_u32 v[146:147], s[60:61], v163, s33, v[6:7]
	v_mad_u64_u32 v[148:149], s[60:61], v166, s33, v[6:7]
	v_mad_u64_u32 v[150:151], s[60:61], v165, s33, v[6:7]
	v_mad_u64_u32 v[152:153], s[60:61], v168, s33, v[6:7]
	v_mad_u64_u32 v[154:155], s[60:61], v167, s33, v[6:7]
	v_mad_u64_u32 v[156:157], s[60:61], v170, s33, v[6:7]
	v_mad_u64_u32 v[158:159], s[60:61], v169, s33, v[6:7]
	s_lshl_b32 s59, s36, 1
	s_lshl_b32 s60, s37, 1
	v_or_b32_e32 v4, s59, v1
	v_or_b32_e32 v9, s60, v2
	s_add_i32 s61, s59, 4
	s_add_i32 s62, s60, 4
	s_add_i32 s63, s59, 8
	s_add_i32 s64, s60, 8
	s_add_i32 s65, s59, 12
	s_add_i32 s66, s60, 12
	s_add_i32 s67, s59, 16
	s_add_i32 s68, s60, 16
	s_add_i32 s69, s59, 20
	s_add_i32 s70, s60, 20
	s_add_i32 s71, s59, 24
	s_add_i32 s72, s60, 24
	s_add_i32 s59, s59, 28
	s_add_i32 s60, s60, 28
	v_add_u32_e32 v30, v9, v14
	v_or_b32_e32 v11, s61, v1
	v_or_b32_e32 v15, s62, v2
	v_or_b32_e32 v29, s63, v1
	v_or_b32_e32 v60, s64, v2
	v_or_b32_e32 v61, s65, v1
	v_or_b32_e32 v62, s66, v2
	v_or_b32_e32 v63, s67, v1
	v_or_b32_e32 v64, s68, v2
	v_or_b32_e32 v65, s69, v1
	v_or_b32_e32 v66, s70, v2
	v_or_b32_e32 v67, s71, v1
	v_or_b32_e32 v68, s72, v2
	v_or_b32_e32 v69, s59, v1
	v_or_b32_e32 v70, s60, v2
	v_add_u32_e32 v18, v4, v3
	v_ashrrev_i32_e32 v31, 31, v30
	v_add_u32_e32 v32, v11, v3
	v_add_u32_e32 v34, v15, v14
	v_add_u32_e32 v36, v29, v3
	v_add_u32_e32 v38, v60, v14
	v_add_u32_e32 v40, v61, v3
	v_add_u32_e32 v42, v62, v14
	v_add_u32_e32 v44, v63, v3
	v_add_u32_e32 v46, v64, v14
	v_add_u32_e32 v48, v65, v3
	v_add_u32_e32 v50, v66, v14
	v_add_u32_e32 v52, v67, v3
	v_add_u32_e32 v54, v68, v14
	v_add_u32_e32 v56, v69, v3
	v_add_u32_e32 v58, v70, v14
	v_ashrrev_i32_e32 v19, 31, v18
	v_lshlrev_b64 v[30:31], 13, v[30:31]
	v_ashrrev_i32_e32 v35, 31, v34
	v_ashrrev_i32_e32 v33, 31, v32
	v_ashrrev_i32_e32 v39, 31, v38
	v_ashrrev_i32_e32 v37, 31, v36
	v_ashrrev_i32_e32 v43, 31, v42
	v_ashrrev_i32_e32 v41, 31, v40
	v_ashrrev_i32_e32 v47, 31, v46
	v_ashrrev_i32_e32 v45, 31, v44
	v_ashrrev_i32_e32 v51, 31, v50
	v_ashrrev_i32_e32 v49, 31, v48
	v_ashrrev_i32_e32 v55, 31, v54
	v_ashrrev_i32_e32 v53, 31, v52
	v_ashrrev_i32_e32 v59, 31, v58
	v_ashrrev_i32_e32 v57, 31, v56
	v_lshlrev_b64 v[18:19], 13, v[18:19]
	v_lshl_add_u64 v[30:31], v[16:17], 0, v[30:31]
	v_lshlrev_b64 v[32:33], 13, v[32:33]
	v_lshlrev_b64 v[34:35], 13, v[34:35]
	v_lshlrev_b64 v[36:37], 13, v[36:37]
	v_lshlrev_b64 v[38:39], 13, v[38:39]
	v_lshlrev_b64 v[40:41], 13, v[40:41]
	v_lshlrev_b64 v[42:43], 13, v[42:43]
	v_lshlrev_b64 v[44:45], 13, v[44:45]
	v_lshlrev_b64 v[46:47], 13, v[46:47]
	v_lshlrev_b64 v[48:49], 13, v[48:49]
	v_lshlrev_b64 v[50:51], 13, v[50:51]
	v_lshlrev_b64 v[52:53], 13, v[52:53]
	v_lshlrev_b64 v[54:55], 13, v[54:55]
	v_lshlrev_b64 v[56:57], 13, v[56:57]
	v_lshlrev_b64 v[58:59], 13, v[58:59]
	v_lshl_add_u64 v[18:19], v[16:17], 0, v[18:19]
	v_lshl_add_u64 v[34:35], v[16:17], 0, v[34:35]
	v_lshl_add_u64 v[32:33], v[16:17], 0, v[32:33]
	v_lshl_add_u64 v[38:39], v[16:17], 0, v[38:39]
	v_lshl_add_u64 v[36:37], v[16:17], 0, v[36:37]
	v_lshl_add_u64 v[42:43], v[16:17], 0, v[42:43]
	v_lshl_add_u64 v[40:41], v[16:17], 0, v[40:41]
	v_lshl_add_u64 v[46:47], v[16:17], 0, v[46:47]
	v_lshl_add_u64 v[44:45], v[16:17], 0, v[44:45]
	v_lshl_add_u64 v[50:51], v[16:17], 0, v[50:51]
	v_lshl_add_u64 v[48:49], v[16:17], 0, v[48:49]
	v_lshl_add_u64 v[54:55], v[16:17], 0, v[54:55]
	v_lshl_add_u64 v[52:53], v[16:17], 0, v[52:53]
	v_lshl_add_u64 v[58:59], v[16:17], 0, v[58:59]
	v_lshl_add_u64 v[56:57], v[16:17], 0, v[56:57]
	global_load_dword v71, v[30:31], off nt
	global_load_dword v72, v[18:19], off nt
	global_load_dword v73, v[34:35], off nt
	global_load_dword v74, v[32:33], off nt
	global_load_dword v75, v[38:39], off nt
	global_load_dword v76, v[36:37], off nt
	global_load_dword v77, v[42:43], off nt
	global_load_dword v78, v[40:41], off nt
	global_load_dword v79, v[46:47], off nt
	global_load_dword v80, v[44:45], off nt
	global_load_dword v81, v[50:51], off nt
	global_load_dword v82, v[48:49], off nt
	global_load_dword v83, v[54:55], off nt
	global_load_dword v84, v[52:53], off nt
	global_load_dword v85, v[58:59], off nt
	global_load_dword v86, v[56:57], off nt
	s_add_i32 s37, s37, 16
	s_add_i32 s36, s36, 16
	s_add_i32 s58, s58, -16
	v_mad_u64_u32 v[18:19], s[60:61], v9, s33, v[6:7]
	v_mad_u64_u32 v[30:31], s[60:61], v4, s33, v[6:7]
	v_mad_u64_u32 v[32:33], s[60:61], v15, s33, v[6:7]
	v_mad_u64_u32 v[34:35], s[60:61], v11, s33, v[6:7]
	v_mad_u64_u32 v[36:37], s[60:61], v60, s33, v[6:7]
	v_mad_u64_u32 v[38:39], s[60:61], v29, s33, v[6:7]
	v_mad_u64_u32 v[40:41], s[60:61], v62, s33, v[6:7]
	v_mad_u64_u32 v[42:43], s[60:61], v61, s33, v[6:7]
	v_mad_u64_u32 v[44:45], s[60:61], v64, s33, v[6:7]
	v_mad_u64_u32 v[46:47], s[60:61], v63, s33, v[6:7]
	v_mad_u64_u32 v[48:49], s[60:61], v66, s33, v[6:7]
	v_mad_u64_u32 v[50:51], s[60:61], v65, s33, v[6:7]
	v_mad_u64_u32 v[52:53], s[60:61], v68, s33, v[6:7]
	v_mad_u64_u32 v[54:55], s[60:61], v67, s33, v[6:7]
	v_mad_u64_u32 v[56:57], s[60:61], v70, s33, v[6:7]
	v_mad_u64_u32 v[58:59], s[60:61], v69, s33, v[6:7]
	s_waitcnt vmcnt(31)
	ds_write_b32 v118, v171
	s_waitcnt vmcnt(30)
	ds_write_b32 v130, v172
	s_waitcnt vmcnt(29)
	ds_write_b32 v132, v173
	s_waitcnt vmcnt(28)
	ds_write_b32 v134, v174
	s_waitcnt vmcnt(27)
	ds_write_b32 v136, v175
	s_waitcnt vmcnt(26)
	ds_write_b32 v138, v176
	s_waitcnt vmcnt(25)
	ds_write_b32 v140, v177
	s_waitcnt vmcnt(24)
	ds_write_b32 v142, v178
	s_waitcnt vmcnt(23)
	ds_write_b32 v144, v179
	s_waitcnt vmcnt(22)
	ds_write_b32 v146, v180
	s_waitcnt vmcnt(21)
	ds_write_b32 v148, v181
	s_waitcnt vmcnt(20)
	ds_write_b32 v150, v182
	s_waitcnt vmcnt(19)
	ds_write_b32 v152, v183
	s_waitcnt vmcnt(18)
	ds_write_b32 v154, v184
	s_waitcnt vmcnt(17)
	ds_write_b32 v156, v185
	s_waitcnt vmcnt(16)
	ds_write_b32 v158, v186
	s_waitcnt vmcnt(15)
	ds_write_b32 v18, v71
	s_waitcnt vmcnt(14)
	ds_write_b32 v30, v72
	s_waitcnt vmcnt(13)
	ds_write_b32 v32, v73
	s_waitcnt vmcnt(12)
	ds_write_b32 v34, v74
	s_waitcnt vmcnt(11)
	ds_write_b32 v36, v75
	s_waitcnt vmcnt(10)
	ds_write_b32 v38, v76
	s_waitcnt vmcnt(9)
	ds_write_b32 v40, v77
	s_waitcnt vmcnt(8)
	ds_write_b32 v42, v78
	s_waitcnt vmcnt(7)
	ds_write_b32 v44, v79
	s_waitcnt vmcnt(6)
	ds_write_b32 v46, v80
	s_waitcnt vmcnt(5)
	ds_write_b32 v48, v81
	s_waitcnt vmcnt(4)
	ds_write_b32 v50, v82
	s_waitcnt vmcnt(3)
	ds_write_b32 v52, v83
	s_waitcnt vmcnt(2)
	ds_write_b32 v54, v84
	s_waitcnt vmcnt(1)
	ds_write_b32 v56, v85
	s_waitcnt vmcnt(0)
	ds_write_b32 v58, v86
	s_waitcnt lgkmcnt(0)
	ds_read2_b32 v[18:19], v22 offset1:8
	ds_read2_b32 v[32:33], v22 offset0:33 offset1:41
	ds_read2_b32 v[34:35], v22 offset0:66 offset1:74
	ds_read2_b32 v[36:37], v22 offset0:99 offset1:107
	v_mov_b64_e32 v[16:17], s[12:13]
	s_waitcnt lgkmcnt(3)
	v_bfe_u32 v3, v18, 16, 1
	v_mad_i64_i32 v[16:17], s[36:37], v12, s50, v[16:17]
	v_mov_b32_e32 v15, v5
	v_add3_u32 v3, v18, v3, s45
	s_waitcnt lgkmcnt(2)
	v_bfe_u32 v4, v32, 16, 1
	ds_read2_b32 v[38:39], v22 offset0:132 offset1:140
	v_lshl_add_u64 v[14:15], v[14:15], 1, v[16:17]
	v_mov_b32_e32 v11, v5
	v_lshrrev_b32_e32 v3, 16, v3
	v_add3_u32 v4, v32, v4, s45
	ds_read2_b32 v[40:41], v22 offset0:165 offset1:173
	v_lshl_add_u64 v[30:31], v[14:15], 0, v[10:11]
	v_and_or_b32 v14, v4, s46, v3
	s_waitcnt lgkmcnt(3)
	v_bfe_u32 v3, v34, 16, 1
	v_add3_u32 v3, v34, v3, s45
	s_waitcnt lgkmcnt(2)
	v_bfe_u32 v4, v36, 16, 1
	ds_read2_b32 v[42:43], v22 offset0:198 offset1:206
	v_lshrrev_b32_e32 v3, 16, v3
	v_add3_u32 v4, v36, v4, s45
	ds_read2_b32 v[44:45], v22 offset0:231 offset1:239
	v_and_or_b32 v15, v4, s46, v3
	s_waitcnt lgkmcnt(3)
	v_bfe_u32 v3, v38, 16, 1
	v_add3_u32 v3, v38, v3, s45
	s_waitcnt lgkmcnt(2)
	v_bfe_u32 v4, v40, 16, 1
	v_lshrrev_b32_e32 v3, 16, v3
	v_add3_u32 v4, v40, v4, s45
	v_and_or_b32 v16, v4, s46, v3
	s_waitcnt lgkmcnt(1)
	v_bfe_u32 v3, v42, 16, 1
	v_add3_u32 v3, v42, v3, s45
	s_waitcnt lgkmcnt(0)
	v_bfe_u32 v4, v44, 16, 1
	v_lshrrev_b32_e32 v3, 16, v3
	v_add3_u32 v4, v44, v4, s45
	v_and_or_b32 v17, v4, s46, v3
	v_or_b32_e32 v3, v13, v21
	v_mul_u32_u24_e32 v3, 0x1600, v3
	v_lshlrev_b32_e32 v4, 1, v3
	v_bfe_u32 v3, v19, 16, 1
	v_lshl_add_u64 v[46:47], v[30:31], 0, v[4:5]
	v_add3_u32 v3, v19, v3, s45
	v_bfe_u32 v4, v33, 16, 1
	v_lshrrev_b32_e32 v3, 16, v3
	v_add3_u32 v4, v33, v4, s45
	global_store_dwordx4 v[46:47], v[14:17], off nt
	ds_read2_b32 v[18:19], v22 offset0:16 offset1:24
	v_readlane_b32 s66, v253, 1
	v_and_or_b32 v14, v4, s46, v3
	v_bfe_u32 v3, v35, 16, 1
	v_add3_u32 v3, v35, v3, s45
	v_bfe_u32 v4, v37, 16, 1
	v_lshrrev_b32_e32 v3, 16, v3
	v_add3_u32 v4, v37, v4, s45
	v_and_or_b32 v15, v4, s46, v3
	v_bfe_u32 v3, v39, 16, 1
	v_add3_u32 v3, v39, v3, s45
	v_bfe_u32 v4, v41, 16, 1
	v_lshrrev_b32_e32 v3, 16, v3
	v_add3_u32 v4, v41, v4, s45
	v_and_or_b32 v16, v4, s46, v3
	v_bfe_u32 v3, v43, 16, 1
	v_add3_u32 v3, v43, v3, s45
	v_bfe_u32 v4, v45, 16, 1
	v_lshrrev_b32_e32 v3, 16, v3
	v_add3_u32 v4, v45, v4, s45
	v_and_or_b32 v17, v4, s46, v3
	v_or_b32_e32 v3, v13, v23
	v_mul_u32_u24_e32 v3, 0x1600, v3
	v_lshlrev_b32_e32 v4, 1, v3
	v_lshl_add_u64 v[32:33], v[30:31], 0, v[4:5]
	global_store_dwordx4 v[32:33], v[14:17], off nt
	ds_read2_b32 v[32:33], v22 offset0:49 offset1:57
	ds_read2_b32 v[34:35], v22 offset0:82 offset1:90
	ds_read2_b32 v[36:37], v22 offset0:115 offset1:123
	s_waitcnt lgkmcnt(3)
	v_bfe_u32 v3, v18, 16, 1
	v_add3_u32 v3, v18, v3, s45
	s_waitcnt lgkmcnt(2)
	v_bfe_u32 v4, v32, 16, 1
	ds_read2_b32 v[38:39], v22 offset0:148 offset1:156
	v_lshrrev_b32_e32 v3, 16, v3
	v_add3_u32 v4, v32, v4, s45
	ds_read2_b32 v[40:41], v22 offset0:181 offset1:189
	v_and_or_b32 v14, v4, s46, v3
	s_waitcnt lgkmcnt(3)
	v_bfe_u32 v3, v34, 16, 1
	v_add3_u32 v3, v34, v3, s45
	s_waitcnt lgkmcnt(2)
	v_bfe_u32 v4, v36, 16, 1
	ds_read2_b32 v[42:43], v22 offset0:214 offset1:222
	v_lshrrev_b32_e32 v3, 16, v3
	v_add3_u32 v4, v36, v4, s45
	ds_read2_b32 v[44:45], v22 offset0:247 offset1:255
	v_and_or_b32 v15, v4, s46, v3
	s_waitcnt lgkmcnt(3)
	v_bfe_u32 v3, v38, 16, 1
	v_add3_u32 v3, v38, v3, s45
	s_waitcnt lgkmcnt(2)
	v_bfe_u32 v4, v40, 16, 1
	v_lshrrev_b32_e32 v3, 16, v3
	v_add3_u32 v4, v40, v4, s45
	v_and_or_b32 v16, v4, s46, v3
	s_waitcnt lgkmcnt(1)
	v_bfe_u32 v3, v42, 16, 1
	v_add3_u32 v3, v42, v3, s45
	s_waitcnt lgkmcnt(0)
	v_bfe_u32 v4, v44, 16, 1
	v_lshrrev_b32_e32 v3, 16, v3
	v_add3_u32 v4, v44, v4, s45
	v_and_or_b32 v17, v4, s46, v3
	v_or_b32_e32 v3, v13, v24
	v_mul_u32_u24_e32 v3, 0x1600, v3
	v_lshlrev_b32_e32 v4, 1, v3
	v_bfe_u32 v3, v19, 16, 1
	v_lshl_add_u64 v[46:47], v[30:31], 0, v[4:5]
	v_add3_u32 v3, v19, v3, s45
	v_bfe_u32 v4, v33, 16, 1
	v_lshrrev_b32_e32 v3, 16, v3
	v_add3_u32 v4, v33, v4, s45
	global_store_dwordx4 v[46:47], v[14:17], off nt
	s_nop 1
	v_and_or_b32 v14, v4, s46, v3
	v_bfe_u32 v3, v35, 16, 1
	v_add3_u32 v3, v35, v3, s45
	v_bfe_u32 v4, v37, 16, 1
	v_lshrrev_b32_e32 v3, 16, v3
	v_add3_u32 v4, v37, v4, s45
	v_and_or_b32 v15, v4, s46, v3
	v_bfe_u32 v3, v39, 16, 1
	v_add3_u32 v3, v39, v3, s45
	v_bfe_u32 v4, v41, 16, 1
	v_lshrrev_b32_e32 v3, 16, v3
	v_add3_u32 v4, v41, v4, s45
	v_and_or_b32 v16, v4, s46, v3
	v_bfe_u32 v3, v43, 16, 1
	v_add3_u32 v3, v43, v3, s45
	v_bfe_u32 v4, v45, 16, 1
	v_lshrrev_b32_e32 v3, 16, v3
	v_add3_u32 v4, v45, v4, s45
	v_and_or_b32 v17, v4, s46, v3
	v_or_b32_e32 v3, v13, v25
	v_mul_u32_u24_e32 v3, 0x1600, v3
	v_lshlrev_b32_e32 v4, 1, v3
	v_lshl_add_u64 v[12:13], v[30:31], 0, v[4:5]
	global_store_dwordx4 v[12:13], v[14:17], off nt
	s_waitcnt lgkmcnt(0)

.LBB0_125:
	s_andn2_saveexec_b64 s[30:31], s[30:31]
	s_cbranch_execz .LBB0_129
	s_load_dwordx2 s[34:35], s[6:7], 0x98
	v_add_u16_e32 v3, 0xd1c0, v3
	v_mul_u32_u24_e32 v4, 0xba2f, v3
	v_lshrrev_b32_e32 v4, 23, v4
	v_mul_lo_u16_e32 v9, 0xb0, v4
	v_sub_u16_e32 v13, v3, v9
	s_waitcnt lgkmcnt(0)
	v_mov_b64_e32 v[16:17], s[34:35]
	v_mad_i64_i32 v[14:15], s[36:37], v12, s49, 0
	v_mad_i64_i32 v[16:17], s[34:35], v12, s49, v[16:17]
	v_lshlrev_b16_e32 v12, 6, v4
	v_lshlrev_b32_e32 v4, 7, v13
	v_lshl_add_u64 v[16:17], v[16:17], 0, v[4:5]
	v_mov_b32_e32 v9, v5
	v_lshlrev_b32_e32 v11, 5, v13
	v_lshl_add_u64 v[16:17], v[16:17], 0, v[8:9]
	v_mov_b32_e32 v3, v12
	s_mov_b32 s34, 1
	s_mov_b32 s35, 0
	s_mov_b32 s36, 32
	s_lshl_b32 s37, s34, 1
	s_lshl_b32 s58, s35, 1
	v_or_b32_e32 v104, s37, v1
	v_or_b32_e32 v109, s58, v2
	s_add_i32 s59, s37, 4
	s_add_i32 s60, s58, 4
	s_add_i32 s61, s37, 8
	s_add_i32 s62, s58, 8
	s_add_i32 s63, s37, 12
	s_add_i32 s64, s58, 12
	s_add_i32 s65, s37, 16
	s_add_i32 s66, s58, 16
	s_add_i32 s67, s37, 20
	s_add_i32 s68, s58, 20
	s_add_i32 s69, s37, 24
	s_add_i32 s70, s58, 24
	s_add_i32 s37, s37, 28
	s_add_i32 s58, s58, 28
	v_add_u32_e32 v129, v104, v3
	v_add_u32_e32 v118, v109, v12
	v_or_b32_e32 v160, s59, v1
	v_or_b32_e32 v161, s60, v2
	v_or_b32_e32 v162, s61, v1
	v_or_b32_e32 v163, s62, v2
	v_or_b32_e32 v164, s63, v1
	v_or_b32_e32 v165, s64, v2
	v_or_b32_e32 v166, s65, v1
	v_or_b32_e32 v167, s66, v2
	v_or_b32_e32 v168, s67, v1
	v_or_b32_e32 v169, s68, v2
	v_or_b32_e32 v170, s69, v1
	v_or_b32_e32 v171, s70, v2
	v_or_b32_e32 v172, s37, v1
	v_or_b32_e32 v173, s58, v2
	v_mad_u64_u32 v[118:119], s[58:59], v118, s51, v[16:17]
	v_mad_u64_u32 v[130:131], s[58:59], v129, s51, v[16:17]
	v_add_u32_e32 v129, v160, v3
	v_add_u32_e32 v132, v161, v12
	v_add_u32_e32 v138, v162, v3
	v_add_u32_e32 v136, v163, v12
	v_add_u32_e32 v142, v164, v3
	v_add_u32_e32 v140, v165, v12
	v_add_u32_e32 v146, v166, v3
	v_add_u32_e32 v144, v167, v12
	v_add_u32_e32 v150, v168, v3
	v_add_u32_e32 v148, v169, v12
	v_add_u32_e32 v154, v170, v3
	v_add_u32_e32 v152, v171, v12
	v_add_u32_e32 v158, v172, v3
	v_add_u32_e32 v156, v173, v12
	v_mad_u64_u32 v[132:133], s[58:59], v132, s51, v[16:17]
	v_mad_u64_u32 v[134:135], s[58:59], v129, s51, v[16:17]
	v_mad_u64_u32 v[136:137], s[58:59], v136, s51, v[16:17]
	v_mad_u64_u32 v[138:139], s[58:59], v138, s51, v[16:17]
	v_mad_u64_u32 v[140:141], s[58:59], v140, s51, v[16:17]
	v_mad_u64_u32 v[142:143], s[58:59], v142, s51, v[16:17]
	v_mad_u64_u32 v[144:145], s[58:59], v144, s51, v[16:17]
	v_mad_u64_u32 v[146:147], s[58:59], v146, s51, v[16:17]
	v_mad_u64_u32 v[148:149], s[58:59], v148, s51, v[16:17]
	v_mad_u64_u32 v[150:151], s[58:59], v150, s51, v[16:17]
	v_mad_u64_u32 v[152:153], s[58:59], v152, s51, v[16:17]
	v_mad_u64_u32 v[154:155], s[58:59], v154, s51, v[16:17]
	v_mad_u64_u32 v[156:157], s[58:59], v156, s51, v[16:17]
	v_mad_u64_u32 v[158:159], s[58:59], v158, s51, v[16:17]
	global_load_dword v129, v[118:119], off nt
	global_load_dword v174, v[130:131], off nt
	global_load_dword v175, v[132:133], off nt
	global_load_dword v176, v[134:135], off nt
	global_load_dword v177, v[136:137], off nt
	global_load_dword v178, v[138:139], off nt
	global_load_dword v179, v[140:141], off nt
	global_load_dword v180, v[142:143], off nt
	global_load_dword v181, v[144:145], off nt
	global_load_dword v182, v[146:147], off nt
	global_load_dword v183, v[148:149], off nt
	global_load_dword v184, v[150:151], off nt
	global_load_dword v185, v[152:153], off nt
	global_load_dword v186, v[154:155], off nt
	global_load_dword v187, v[156:157], off nt
	global_load_dword v188, v[158:159], off nt
	s_add_i32 s35, s35, 16
	s_add_i32 s34, s34, 16
	s_add_i32 s36, s36, -16
	v_mad_u64_u32 v[118:119], s[58:59], v109, s33, v[6:7]
	v_mad_u64_u32 v[130:131], s[58:59], v104, s33, v[6:7]
	v_mad_u64_u32 v[132:133], s[58:59], v161, s33, v[6:7]
	v_mad_u64_u32 v[134:135], s[58:59], v160, s33, v[6:7]
	v_mad_u64_u32 v[136:137], s[58:59], v163, s33, v[6:7]
	v_mad_u64_u32 v[138:139], s[58:59], v162, s33, v[6:7]
	v_mad_u64_u32 v[140:141], s[58:59], v165, s33, v[6:7]
	v_mad_u64_u32 v[142:143], s[58:59], v164, s33, v[6:7]
	v_mad_u64_u32 v[144:145], s[58:59], v167, s33, v[6:7]
	v_mad_u64_u32 v[146:147], s[58:59], v166, s33, v[6:7]
	v_mad_u64_u32 v[148:149], s[58:59], v169, s33, v[6:7]
	v_mad_u64_u32 v[150:151], s[58:59], v168, s33, v[6:7]
	v_mad_u64_u32 v[152:153], s[58:59], v171, s33, v[6:7]
	v_mad_u64_u32 v[154:155], s[58:59], v170, s33, v[6:7]
	v_mad_u64_u32 v[156:157], s[58:59], v173, s33, v[6:7]
	v_mad_u64_u32 v[158:159], s[58:59], v172, s33, v[6:7]
	s_lshl_b32 s37, s34, 1
	s_lshl_b32 s58, s35, 1
	v_or_b32_e32 v4, s37, v1
	v_or_b32_e32 v9, s58, v2
	s_add_i32 s59, s37, 4
	s_add_i32 s60, s58, 4
	s_add_i32 s61, s37, 8
	s_add_i32 s62, s58, 8
	s_add_i32 s63, s37, 12
	s_add_i32 s64, s58, 12
	s_add_i32 s65, s37, 16
	s_add_i32 s66, s58, 16
	s_add_i32 s67, s37, 20
	s_add_i32 s68, s58, 20
	s_add_i32 s69, s37, 24
	s_add_i32 s70, s58, 24
	s_add_i32 s37, s37, 28
	s_add_i32 s58, s58, 28
	v_add_u32_e32 v29, v4, v3
	v_add_u32_e32 v18, v9, v12
	v_or_b32_e32 v60, s59, v1
	v_or_b32_e32 v61, s60, v2
	v_or_b32_e32 v62, s61, v1
	v_or_b32_e32 v63, s62, v2
	v_or_b32_e32 v64, s63, v1
	v_or_b32_e32 v65, s64, v2
	v_or_b32_e32 v66, s65, v1
	v_or_b32_e32 v67, s66, v2
	v_or_b32_e32 v68, s67, v1
	v_or_b32_e32 v69, s68, v2
	v_or_b32_e32 v70, s69, v1
	v_or_b32_e32 v71, s70, v2
	v_or_b32_e32 v72, s37, v1
	v_or_b32_e32 v73, s58, v2
	v_mad_u64_u32 v[18:19], s[58:59], v18, s51, v[16:17]
	v_mad_u64_u32 v[30:31], s[58:59], v29, s51, v[16:17]
	v_add_u32_e32 v29, v60, v3
	v_add_u32_e32 v32, v61, v12
	v_add_u32_e32 v38, v62, v3
	v_add_u32_e32 v36, v63, v12
	v_add_u32_e32 v42, v64, v3
	v_add_u32_e32 v40, v65, v12
	v_add_u32_e32 v46, v66, v3
	v_add_u32_e32 v44, v67, v12
	v_add_u32_e32 v50, v68, v3
	v_add_u32_e32 v48, v69, v12
	v_add_u32_e32 v54, v70, v3
	v_add_u32_e32 v52, v71, v12
	v_add_u32_e32 v58, v72, v3
	v_add_u32_e32 v56, v73, v12
	v_mad_u64_u32 v[32:33], s[58:59], v32, s51, v[16:17]
	v_mad_u64_u32 v[34:35], s[58:59], v29, s51, v[16:17]
	v_mad_u64_u32 v[36:37], s[58:59], v36, s51, v[16:17]
	v_mad_u64_u32 v[38:39], s[58:59], v38, s51, v[16:17]
	v_mad_u64_u32 v[40:41], s[58:59], v40, s51, v[16:17]
	v_mad_u64_u32 v[42:43], s[58:59], v42, s51, v[16:17]
	v_mad_u64_u32 v[44:45], s[58:59], v44, s51, v[16:17]
	v_mad_u64_u32 v[46:47], s[58:59], v46, s51, v[16:17]
	v_mad_u64_u32 v[48:49], s[58:59], v48, s51, v[16:17]
	v_mad_u64_u32 v[50:51], s[58:59], v50, s51, v[16:17]
	v_mad_u64_u32 v[52:53], s[58:59], v52, s51, v[16:17]
	v_mad_u64_u32 v[54:55], s[58:59], v54, s51, v[16:17]
	v_mad_u64_u32 v[56:57], s[58:59], v56, s51, v[16:17]
	v_mad_u64_u32 v[58:59], s[58:59], v58, s51, v[16:17]
	global_load_dword v29, v[18:19], off nt
	global_load_dword v74, v[30:31], off nt
	global_load_dword v75, v[32:33], off nt
	global_load_dword v76, v[34:35], off nt
	global_load_dword v77, v[36:37], off nt
	global_load_dword v78, v[38:39], off nt
	global_load_dword v79, v[40:41], off nt
	global_load_dword v80, v[42:43], off nt
	global_load_dword v81, v[44:45], off nt
	global_load_dword v82, v[46:47], off nt
	global_load_dword v83, v[48:49], off nt
	global_load_dword v84, v[50:51], off nt
	global_load_dword v85, v[52:53], off nt
	global_load_dword v86, v[54:55], off nt
	global_load_dword v87, v[56:57], off nt
	global_load_dword v88, v[58:59], off nt
	s_add_i32 s35, s35, 16
	s_add_i32 s34, s34, 16
	s_add_i32 s36, s36, -16
	v_mad_u64_u32 v[18:19], s[58:59], v9, s33, v[6:7]
	v_mad_u64_u32 v[30:31], s[58:59], v4, s33, v[6:7]
	v_mad_u64_u32 v[32:33], s[58:59], v61, s33, v[6:7]
	v_mad_u64_u32 v[34:35], s[58:59], v60, s33, v[6:7]
	v_mad_u64_u32 v[36:37], s[58:59], v63, s33, v[6:7]
	v_mad_u64_u32 v[38:39], s[58:59], v62, s33, v[6:7]
	v_mad_u64_u32 v[40:41], s[58:59], v65, s33, v[6:7]
	v_mad_u64_u32 v[42:43], s[58:59], v64, s33, v[6:7]
	v_mad_u64_u32 v[44:45], s[58:59], v67, s33, v[6:7]
	v_mad_u64_u32 v[46:47], s[58:59], v66, s33, v[6:7]
	v_mad_u64_u32 v[48:49], s[58:59], v69, s33, v[6:7]
	v_mad_u64_u32 v[50:51], s[58:59], v68, s33, v[6:7]
	v_mad_u64_u32 v[52:53], s[58:59], v71, s33, v[6:7]
	v_mad_u64_u32 v[54:55], s[58:59], v70, s33, v[6:7]
	v_mad_u64_u32 v[56:57], s[58:59], v73, s33, v[6:7]
	v_mad_u64_u32 v[58:59], s[58:59], v72, s33, v[6:7]
	s_waitcnt vmcnt(31)
	ds_write_b32 v118, v129
	s_waitcnt vmcnt(30)
	ds_write_b32 v130, v174
	s_waitcnt vmcnt(29)
	ds_write_b32 v132, v175
	s_waitcnt vmcnt(28)
	ds_write_b32 v134, v176
	s_waitcnt vmcnt(27)
	ds_write_b32 v136, v177
	s_waitcnt vmcnt(26)
	ds_write_b32 v138, v178
	s_waitcnt vmcnt(25)
	ds_write_b32 v140, v179
	s_waitcnt vmcnt(24)
	ds_write_b32 v142, v180
	s_waitcnt vmcnt(23)
	ds_write_b32 v144, v181
	s_waitcnt vmcnt(22)
	ds_write_b32 v146, v182
	s_waitcnt vmcnt(21)
	ds_write_b32 v148, v183
	s_waitcnt vmcnt(20)
	ds_write_b32 v150, v184
	s_waitcnt vmcnt(19)
	ds_write_b32 v152, v185
	s_waitcnt vmcnt(18)
	ds_write_b32 v154, v186
	s_waitcnt vmcnt(17)
	ds_write_b32 v156, v187
	s_waitcnt vmcnt(16)
	ds_write_b32 v158, v188
	s_waitcnt vmcnt(15)
	ds_write_b32 v18, v29
	s_waitcnt vmcnt(14)
	ds_write_b32 v30, v74
	s_waitcnt vmcnt(13)
	ds_write_b32 v32, v75
	s_waitcnt vmcnt(12)
	ds_write_b32 v34, v76
	s_waitcnt vmcnt(11)
	ds_write_b32 v36, v77
	s_waitcnt vmcnt(10)
	ds_write_b32 v38, v78
	s_waitcnt vmcnt(9)
	ds_write_b32 v40, v79
	s_waitcnt vmcnt(8)
	ds_write_b32 v42, v80
	s_waitcnt vmcnt(7)
	ds_write_b32 v44, v81
	s_waitcnt vmcnt(6)
	ds_write_b32 v46, v82
	s_waitcnt vmcnt(5)
	ds_write_b32 v48, v83
	s_waitcnt vmcnt(4)
	ds_write_b32 v50, v84
	s_waitcnt vmcnt(3)
	ds_write_b32 v52, v85
	s_waitcnt vmcnt(2)
	ds_write_b32 v54, v86
	s_waitcnt vmcnt(1)
	ds_write_b32 v56, v87
	s_waitcnt vmcnt(0)
	ds_write_b32 v58, v88
	s_waitcnt lgkmcnt(0)
	ds_read2_b32 v[16:17], v22 offset1:8
	ds_read2_b32 v[30:31], v22 offset0:33 offset1:41
	v_lshlrev_b32_e32 v3, 6, v13
	v_and_b32_e32 v3, 0x3f00, v3
	v_and_b32_e32 v4, 0x60, v11
	ds_read2_b32 v[32:33], v22 offset0:66 offset1:74
	v_lshl_add_u64 v[14:15], s[14:15], 0, v[14:15]
	v_or3_b32 v3, v3, v4, s53
	v_lshlrev_b32_e32 v4, 1, v12
	ds_read2_b32 v[34:35], v22 offset0:99 offset1:107
	v_lshl_add_u64 v[12:13], v[14:15], 0, v[4:5]
	s_waitcnt lgkmcnt(3)
	v_bfe_u32 v4, v16, 16, 1
	v_add3_u32 v4, v16, v4, s45
	s_waitcnt lgkmcnt(2)
	v_bfe_u32 v9, v30, 16, 1
	ds_read2_b32 v[36:37], v22 offset0:132 offset1:140
	v_mov_b32_e32 v11, v5
	v_lshrrev_b32_e32 v4, 16, v4
	v_add3_u32 v9, v30, v9, s45
	ds_read2_b32 v[38:39], v22 offset0:165 offset1:173
	v_lshl_add_u64 v[18:19], v[12:13], 0, v[10:11]
	v_and_or_b32 v12, v9, s46, v4
	s_waitcnt lgkmcnt(3)
	v_bfe_u32 v4, v32, 16, 1
	v_add3_u32 v4, v32, v4, s45
	s_waitcnt lgkmcnt(2)
	v_bfe_u32 v9, v34, 16, 1
	ds_read2_b32 v[40:41], v22 offset0:198 offset1:206
	v_lshrrev_b32_e32 v4, 16, v4
	v_add3_u32 v9, v34, v9, s45
	ds_read2_b32 v[42:43], v22 offset0:231 offset1:239
	v_and_or_b32 v13, v9, s46, v4
	s_waitcnt lgkmcnt(3)
	v_bfe_u32 v4, v36, 16, 1
	v_add3_u32 v4, v36, v4, s45
	s_waitcnt lgkmcnt(2)
	v_bfe_u32 v9, v38, 16, 1
	v_lshrrev_b32_e32 v4, 16, v4
	v_add3_u32 v9, v38, v9, s45
	v_and_or_b32 v14, v9, s46, v4
	s_waitcnt lgkmcnt(1)
	v_bfe_u32 v4, v40, 16, 1
	v_add3_u32 v4, v40, v4, s45
	s_waitcnt lgkmcnt(0)
	v_bfe_u32 v9, v42, 16, 1
	v_lshrrev_b32_e32 v4, 16, v4
	v_add3_u32 v9, v42, v9, s45
	v_and_or_b32 v15, v9, s46, v4
	v_or_b32_e32 v4, v3, v21
	v_lshlrev_b32_e32 v4, 12, v4
	v_lshl_add_u64 v[44:45], v[18:19], 0, v[4:5]
	v_bfe_u32 v4, v17, 16, 1
	v_add3_u32 v4, v17, v4, s45
	v_bfe_u32 v9, v31, 16, 1
	v_lshrrev_b32_e32 v4, 16, v4
	v_add3_u32 v9, v31, v9, s45
	global_store_dwordx4 v[44:45], v[12:15], off nt
	ds_read2_b32 v[16:17], v22 offset0:16 offset1:24
	v_readlane_b32 s66, v253, 1
	v_and_or_b32 v12, v9, s46, v4
	v_bfe_u32 v4, v33, 16, 1
	v_add3_u32 v4, v33, v4, s45
	v_bfe_u32 v9, v35, 16, 1
	v_lshrrev_b32_e32 v4, 16, v4
	v_add3_u32 v9, v35, v9, s45
	v_and_or_b32 v13, v9, s46, v4
	v_bfe_u32 v4, v37, 16, 1
	v_add3_u32 v4, v37, v4, s45
	v_bfe_u32 v9, v39, 16, 1
	v_lshrrev_b32_e32 v4, 16, v4
	v_add3_u32 v9, v39, v9, s45
	v_and_or_b32 v14, v9, s46, v4
	v_bfe_u32 v4, v41, 16, 1
	v_add3_u32 v4, v41, v4, s45
	v_bfe_u32 v9, v43, 16, 1
	v_lshrrev_b32_e32 v4, 16, v4
	v_add3_u32 v9, v43, v9, s45
	v_and_or_b32 v15, v9, s46, v4
	v_or_b32_e32 v4, v3, v23
	v_lshlrev_b32_e32 v4, 12, v4
	v_lshl_add_u64 v[30:31], v[18:19], 0, v[4:5]
	global_store_dwordx4 v[30:31], v[12:15], off nt
	ds_read2_b32 v[30:31], v22 offset0:49 offset1:57
	ds_read2_b32 v[32:33], v22 offset0:82 offset1:90
	ds_read2_b32 v[34:35], v22 offset0:115 offset1:123
	s_waitcnt lgkmcnt(3)
	v_bfe_u32 v4, v16, 16, 1
	v_add3_u32 v4, v16, v4, s45
	s_waitcnt lgkmcnt(2)
	v_bfe_u32 v9, v30, 16, 1
	ds_read2_b32 v[36:37], v22 offset0:148 offset1:156
	v_lshrrev_b32_e32 v4, 16, v4
	v_add3_u32 v9, v30, v9, s45
	ds_read2_b32 v[38:39], v22 offset0:181 offset1:189
	v_and_or_b32 v12, v9, s46, v4
	s_waitcnt lgkmcnt(3)
	v_bfe_u32 v4, v32, 16, 1
	v_add3_u32 v4, v32, v4, s45
	s_waitcnt lgkmcnt(2)
	v_bfe_u32 v9, v34, 16, 1
	ds_read2_b32 v[40:41], v22 offset0:214 offset1:222
	v_lshrrev_b32_e32 v4, 16, v4
	v_add3_u32 v9, v34, v9, s45
	ds_read2_b32 v[42:43], v22 offset0:247 offset1:255
	v_and_or_b32 v13, v9, s46, v4
	s_waitcnt lgkmcnt(3)
	v_bfe_u32 v4, v36, 16, 1
	v_add3_u32 v4, v36, v4, s45
	s_waitcnt lgkmcnt(2)
	v_bfe_u32 v9, v38, 16, 1
	v_lshrrev_b32_e32 v4, 16, v4
	v_add3_u32 v9, v38, v9, s45
	v_and_or_b32 v14, v9, s46, v4
	s_waitcnt lgkmcnt(1)
	v_bfe_u32 v4, v40, 16, 1
	v_add3_u32 v4, v40, v4, s45
	s_waitcnt lgkmcnt(0)
	v_bfe_u32 v9, v42, 16, 1
	v_lshrrev_b32_e32 v4, 16, v4
	v_add3_u32 v9, v42, v9, s45
	v_and_or_b32 v15, v9, s46, v4
	v_or_b32_e32 v4, v3, v24
	v_lshlrev_b32_e32 v4, 12, v4
	v_lshl_add_u64 v[44:45], v[18:19], 0, v[4:5]
	v_bfe_u32 v4, v17, 16, 1
	v_add3_u32 v4, v17, v4, s45
	v_bfe_u32 v9, v31, 16, 1
	v_lshrrev_b32_e32 v4, 16, v4
	v_add3_u32 v9, v31, v9, s45
	global_store_dwordx4 v[44:45], v[12:15], off nt
	v_or_b32_e32 v3, v3, v25
	s_nop 0
	v_and_or_b32 v12, v9, s46, v4
	v_bfe_u32 v4, v33, 16, 1
	v_add3_u32 v4, v33, v4, s45
	v_bfe_u32 v9, v35, 16, 1
	v_lshrrev_b32_e32 v4, 16, v4
	v_add3_u32 v9, v35, v9, s45
	v_and_or_b32 v13, v9, s46, v4
	v_bfe_u32 v4, v37, 16, 1
	v_add3_u32 v4, v37, v4, s45
	v_bfe_u32 v9, v39, 16, 1
	v_lshrrev_b32_e32 v4, 16, v4
	v_add3_u32 v9, v39, v9, s45
	v_and_or_b32 v14, v9, s46, v4
	v_bfe_u32 v4, v41, 16, 1
	v_add3_u32 v4, v41, v4, s45
	v_bfe_u32 v9, v43, 16, 1
	v_lshrrev_b32_e32 v4, 16, v4
	v_add3_u32 v9, v43, v9, s45
	v_and_or_b32 v15, v9, s46, v4
	v_lshlrev_b32_e32 v4, 12, v3
	v_lshl_add_u64 v[16:17], v[18:19], 0, v[4:5]
	global_store_dwordx4 v[16:17], v[12:15], off nt
	s_waitcnt lgkmcnt(0)

.LBB0_130:
	s_andn2_saveexec_b64 s[28:29], s[28:29]
	s_cbranch_execz .LBB0_134
	s_load_dwordx2 s[30:31], s[6:7], 0x90
	v_add_u16_e32 v3, 0xe7c0, v3
	v_mul_u32_u24_e32 v4, 0xba2f, v3
	v_lshrrev_b32_e32 v4, 23, v4
	v_mul_lo_u16_e32 v9, 0xb0, v4
	v_sub_u16_e32 v11, v3, v9
	s_waitcnt lgkmcnt(0)
	v_mov_b64_e32 v[16:17], s[30:31]
	v_mad_i64_i32 v[14:15], s[34:35], v12, s49, 0
	v_mad_i64_i32 v[16:17], s[30:31], v12, s49, v[16:17]
	v_lshlrev_b16_e32 v12, 6, v4
	v_lshlrev_b32_e32 v4, 7, v11
	v_lshl_add_u64 v[16:17], v[16:17], 0, v[4:5]
	v_mov_b32_e32 v9, v5
	v_lshlrev_b32_e32 v13, 5, v11
	v_lshl_add_u64 v[16:17], v[16:17], 0, v[8:9]
	v_mov_b32_e32 v3, v12
	s_mov_b32 s30, 1
	s_mov_b32 s31, 0
	s_mov_b32 s34, 32
	s_lshl_b32 s35, s30, 1
	s_lshl_b32 s36, s31, 1
	v_or_b32_e32 v104, s35, v1
	v_or_b32_e32 v109, s36, v2
	s_add_i32 s37, s35, 4
	s_add_i32 s58, s36, 4
	s_add_i32 s59, s35, 8
	s_add_i32 s60, s36, 8
	s_add_i32 s61, s35, 12
	s_add_i32 s62, s36, 12
	s_add_i32 s63, s35, 16
	s_add_i32 s64, s36, 16
	s_add_i32 s65, s35, 20
	s_add_i32 s66, s36, 20
	s_add_i32 s67, s35, 24
	s_add_i32 s68, s36, 24
	s_add_i32 s35, s35, 28
	s_add_i32 s36, s36, 28
	v_add_u32_e32 v129, v104, v3
	v_add_u32_e32 v118, v109, v12
	v_or_b32_e32 v160, s37, v1
	v_or_b32_e32 v161, s58, v2
	v_or_b32_e32 v162, s59, v1
	v_or_b32_e32 v163, s60, v2
	v_or_b32_e32 v164, s61, v1
	v_or_b32_e32 v165, s62, v2
	v_or_b32_e32 v166, s63, v1
	v_or_b32_e32 v167, s64, v2
	v_or_b32_e32 v168, s65, v1
	v_or_b32_e32 v169, s66, v2
	v_or_b32_e32 v170, s67, v1
	v_or_b32_e32 v171, s68, v2
	v_or_b32_e32 v172, s35, v1
	v_or_b32_e32 v173, s36, v2
	v_mad_u64_u32 v[118:119], s[36:37], v118, s51, v[16:17]
	v_mad_u64_u32 v[130:131], s[36:37], v129, s51, v[16:17]
	v_add_u32_e32 v129, v160, v3
	v_add_u32_e32 v132, v161, v12
	v_add_u32_e32 v138, v162, v3
	v_add_u32_e32 v136, v163, v12
	v_add_u32_e32 v142, v164, v3
	v_add_u32_e32 v140, v165, v12
	v_add_u32_e32 v146, v166, v3
	v_add_u32_e32 v144, v167, v12
	v_add_u32_e32 v150, v168, v3
	v_add_u32_e32 v148, v169, v12
	v_add_u32_e32 v154, v170, v3
	v_add_u32_e32 v152, v171, v12
	v_add_u32_e32 v158, v172, v3
	v_add_u32_e32 v156, v173, v12
	v_mad_u64_u32 v[132:133], s[36:37], v132, s51, v[16:17]
	v_mad_u64_u32 v[134:135], s[36:37], v129, s51, v[16:17]
	v_mad_u64_u32 v[136:137], s[36:37], v136, s51, v[16:17]
	v_mad_u64_u32 v[138:139], s[36:37], v138, s51, v[16:17]
	v_mad_u64_u32 v[140:141], s[36:37], v140, s51, v[16:17]
	v_mad_u64_u32 v[142:143], s[36:37], v142, s51, v[16:17]
	v_mad_u64_u32 v[144:145], s[36:37], v144, s51, v[16:17]
	v_mad_u64_u32 v[146:147], s[36:37], v146, s51, v[16:17]
	v_mad_u64_u32 v[148:149], s[36:37], v148, s51, v[16:17]
	v_mad_u64_u32 v[150:151], s[36:37], v150, s51, v[16:17]
	v_mad_u64_u32 v[152:153], s[36:37], v152, s51, v[16:17]
	v_mad_u64_u32 v[154:155], s[36:37], v154, s51, v[16:17]
	v_mad_u64_u32 v[156:157], s[36:37], v156, s51, v[16:17]
	v_mad_u64_u32 v[158:159], s[36:37], v158, s51, v[16:17]
	global_load_dword v129, v[118:119], off nt
	global_load_dword v174, v[130:131], off nt
	global_load_dword v175, v[132:133], off nt
	global_load_dword v176, v[134:135], off nt
	global_load_dword v177, v[136:137], off nt
	global_load_dword v178, v[138:139], off nt
	global_load_dword v179, v[140:141], off nt
	global_load_dword v180, v[142:143], off nt
	global_load_dword v181, v[144:145], off nt
	global_load_dword v182, v[146:147], off nt
	global_load_dword v183, v[148:149], off nt
	global_load_dword v184, v[150:151], off nt
	global_load_dword v185, v[152:153], off nt
	global_load_dword v186, v[154:155], off nt
	global_load_dword v187, v[156:157], off nt
	global_load_dword v188, v[158:159], off nt
	s_add_i32 s31, s31, 16
	s_add_i32 s30, s30, 16
	s_add_i32 s34, s34, -16
	v_mad_u64_u32 v[118:119], s[36:37], v109, s33, v[6:7]
	v_mad_u64_u32 v[130:131], s[36:37], v104, s33, v[6:7]
	v_mad_u64_u32 v[132:133], s[36:37], v161, s33, v[6:7]
	v_mad_u64_u32 v[134:135], s[36:37], v160, s33, v[6:7]
	v_mad_u64_u32 v[136:137], s[36:37], v163, s33, v[6:7]
	v_mad_u64_u32 v[138:139], s[36:37], v162, s33, v[6:7]
	v_mad_u64_u32 v[140:141], s[36:37], v165, s33, v[6:7]
	v_mad_u64_u32 v[142:143], s[36:37], v164, s33, v[6:7]
	v_mad_u64_u32 v[144:145], s[36:37], v167, s33, v[6:7]
	v_mad_u64_u32 v[146:147], s[36:37], v166, s33, v[6:7]
	v_mad_u64_u32 v[148:149], s[36:37], v169, s33, v[6:7]
	v_mad_u64_u32 v[150:151], s[36:37], v168, s33, v[6:7]
	v_mad_u64_u32 v[152:153], s[36:37], v171, s33, v[6:7]
	v_mad_u64_u32 v[154:155], s[36:37], v170, s33, v[6:7]
	v_mad_u64_u32 v[156:157], s[36:37], v173, s33, v[6:7]
	v_mad_u64_u32 v[158:159], s[36:37], v172, s33, v[6:7]
	s_lshl_b32 s35, s30, 1
	s_lshl_b32 s36, s31, 1
	v_or_b32_e32 v4, s35, v1
	v_or_b32_e32 v9, s36, v2
	s_add_i32 s37, s35, 4
	s_add_i32 s58, s36, 4
	s_add_i32 s59, s35, 8
	s_add_i32 s60, s36, 8
	s_add_i32 s61, s35, 12
	s_add_i32 s62, s36, 12
	s_add_i32 s63, s35, 16
	s_add_i32 s64, s36, 16
	s_add_i32 s65, s35, 20
	s_add_i32 s66, s36, 20
	s_add_i32 s67, s35, 24
	s_add_i32 s68, s36, 24
	s_add_i32 s35, s35, 28
	s_add_i32 s36, s36, 28
	v_add_u32_e32 v29, v4, v3
	v_add_u32_e32 v18, v9, v12
	v_or_b32_e32 v60, s37, v1
	v_or_b32_e32 v61, s58, v2
	v_or_b32_e32 v62, s59, v1
	v_or_b32_e32 v63, s60, v2
	v_or_b32_e32 v64, s61, v1
	v_or_b32_e32 v65, s62, v2
	v_or_b32_e32 v66, s63, v1
	v_or_b32_e32 v67, s64, v2
	v_or_b32_e32 v68, s65, v1
	v_or_b32_e32 v69, s66, v2
	v_or_b32_e32 v70, s67, v1
	v_or_b32_e32 v71, s68, v2
	v_or_b32_e32 v72, s35, v1
	v_or_b32_e32 v73, s36, v2
	v_mad_u64_u32 v[18:19], s[36:37], v18, s51, v[16:17]
	v_mad_u64_u32 v[30:31], s[36:37], v29, s51, v[16:17]
	v_add_u32_e32 v29, v60, v3
	v_add_u32_e32 v32, v61, v12
	v_add_u32_e32 v38, v62, v3
	v_add_u32_e32 v36, v63, v12
	v_add_u32_e32 v42, v64, v3
	v_add_u32_e32 v40, v65, v12
	v_add_u32_e32 v46, v66, v3
	v_add_u32_e32 v44, v67, v12
	v_add_u32_e32 v50, v68, v3
	v_add_u32_e32 v48, v69, v12
	v_add_u32_e32 v54, v70, v3
	v_add_u32_e32 v52, v71, v12
	v_add_u32_e32 v58, v72, v3
	v_add_u32_e32 v56, v73, v12
	v_mad_u64_u32 v[32:33], s[36:37], v32, s51, v[16:17]
	v_mad_u64_u32 v[34:35], s[36:37], v29, s51, v[16:17]
	v_mad_u64_u32 v[36:37], s[36:37], v36, s51, v[16:17]
	v_mad_u64_u32 v[38:39], s[36:37], v38, s51, v[16:17]
	v_mad_u64_u32 v[40:41], s[36:37], v40, s51, v[16:17]
	v_mad_u64_u32 v[42:43], s[36:37], v42, s51, v[16:17]
	v_mad_u64_u32 v[44:45], s[36:37], v44, s51, v[16:17]
	v_mad_u64_u32 v[46:47], s[36:37], v46, s51, v[16:17]
	v_mad_u64_u32 v[48:49], s[36:37], v48, s51, v[16:17]
	v_mad_u64_u32 v[50:51], s[36:37], v50, s51, v[16:17]
	v_mad_u64_u32 v[52:53], s[36:37], v52, s51, v[16:17]
	v_mad_u64_u32 v[54:55], s[36:37], v54, s51, v[16:17]
	v_mad_u64_u32 v[56:57], s[36:37], v56, s51, v[16:17]
	v_mad_u64_u32 v[58:59], s[36:37], v58, s51, v[16:17]
	global_load_dword v29, v[18:19], off nt
	global_load_dword v74, v[30:31], off nt
	global_load_dword v75, v[32:33], off nt
	global_load_dword v76, v[34:35], off nt
	global_load_dword v77, v[36:37], off nt
	global_load_dword v78, v[38:39], off nt
	global_load_dword v79, v[40:41], off nt
	global_load_dword v80, v[42:43], off nt
	global_load_dword v81, v[44:45], off nt
	global_load_dword v82, v[46:47], off nt
	global_load_dword v83, v[48:49], off nt
	global_load_dword v84, v[50:51], off nt
	global_load_dword v85, v[52:53], off nt
	global_load_dword v86, v[54:55], off nt
	global_load_dword v87, v[56:57], off nt
	global_load_dword v88, v[58:59], off nt
	s_add_i32 s31, s31, 16
	s_add_i32 s30, s30, 16
	s_add_i32 s34, s34, -16
	v_mad_u64_u32 v[18:19], s[36:37], v9, s33, v[6:7]
	v_mad_u64_u32 v[30:31], s[36:37], v4, s33, v[6:7]
	v_mad_u64_u32 v[32:33], s[36:37], v61, s33, v[6:7]
	v_mad_u64_u32 v[34:35], s[36:37], v60, s33, v[6:7]
	v_mad_u64_u32 v[36:37], s[36:37], v63, s33, v[6:7]
	v_mad_u64_u32 v[38:39], s[36:37], v62, s33, v[6:7]
	v_mad_u64_u32 v[40:41], s[36:37], v65, s33, v[6:7]
	v_mad_u64_u32 v[42:43], s[36:37], v64, s33, v[6:7]
	v_mad_u64_u32 v[44:45], s[36:37], v67, s33, v[6:7]
	v_mad_u64_u32 v[46:47], s[36:37], v66, s33, v[6:7]
	v_mad_u64_u32 v[48:49], s[36:37], v69, s33, v[6:7]
	v_mad_u64_u32 v[50:51], s[36:37], v68, s33, v[6:7]
	v_mad_u64_u32 v[52:53], s[36:37], v71, s33, v[6:7]
	v_mad_u64_u32 v[54:55], s[36:37], v70, s33, v[6:7]
	v_mad_u64_u32 v[56:57], s[36:37], v73, s33, v[6:7]
	v_mad_u64_u32 v[58:59], s[36:37], v72, s33, v[6:7]
	s_waitcnt vmcnt(31)
	ds_write_b32 v118, v129
	s_waitcnt vmcnt(30)
	ds_write_b32 v130, v174
	s_waitcnt vmcnt(29)
	ds_write_b32 v132, v175
	s_waitcnt vmcnt(28)
	ds_write_b32 v134, v176
	s_waitcnt vmcnt(27)
	ds_write_b32 v136, v177
	s_waitcnt vmcnt(26)
	ds_write_b32 v138, v178
	s_waitcnt vmcnt(25)
	ds_write_b32 v140, v179
	s_waitcnt vmcnt(24)
	ds_write_b32 v142, v180
	s_waitcnt vmcnt(23)
	ds_write_b32 v144, v181
	s_waitcnt vmcnt(22)
	ds_write_b32 v146, v182
	s_waitcnt vmcnt(21)
	ds_write_b32 v148, v183
	s_waitcnt vmcnt(20)
	ds_write_b32 v150, v184
	s_waitcnt vmcnt(19)
	ds_write_b32 v152, v185
	s_waitcnt vmcnt(18)
	ds_write_b32 v154, v186
	s_waitcnt vmcnt(17)
	ds_write_b32 v156, v187
	s_waitcnt vmcnt(16)
	ds_write_b32 v158, v188
	s_waitcnt vmcnt(15)
	ds_write_b32 v18, v29
	s_waitcnt vmcnt(14)
	ds_write_b32 v30, v74
	s_waitcnt vmcnt(13)
	ds_write_b32 v32, v75
	s_waitcnt vmcnt(12)
	ds_write_b32 v34, v76
	s_waitcnt vmcnt(11)
	ds_write_b32 v36, v77
	s_waitcnt vmcnt(10)
	ds_write_b32 v38, v78
	s_waitcnt vmcnt(9)
	ds_write_b32 v40, v79
	s_waitcnt vmcnt(8)
	ds_write_b32 v42, v80
	s_waitcnt vmcnt(7)
	ds_write_b32 v44, v81
	s_waitcnt vmcnt(6)
	ds_write_b32 v46, v82
	s_waitcnt vmcnt(5)
	ds_write_b32 v48, v83
	s_waitcnt vmcnt(4)
	ds_write_b32 v50, v84
	s_waitcnt vmcnt(3)
	ds_write_b32 v52, v85
	s_waitcnt vmcnt(2)
	ds_write_b32 v54, v86
	s_waitcnt vmcnt(1)
	ds_write_b32 v56, v87
	s_waitcnt vmcnt(0)
	ds_write_b32 v58, v88
	s_waitcnt lgkmcnt(0)
	ds_read2_b32 v[16:17], v22 offset1:8
	ds_read2_b32 v[30:31], v22 offset0:33 offset1:41
	v_lshlrev_b32_e32 v3, 6, v11
	v_and_b32_e32 v4, 0x60, v13
	ds_read2_b32 v[32:33], v22 offset0:66 offset1:74
	v_lshl_add_u64 v[14:15], s[14:15], 0, v[14:15]
	v_and_or_b32 v3, v3, s52, v4
	v_lshlrev_b32_e32 v4, 1, v12
	ds_read2_b32 v[34:35], v22 offset0:99 offset1:107
	v_lshl_add_u64 v[12:13], v[14:15], 0, v[4:5]
	s_waitcnt lgkmcnt(3)
	v_bfe_u32 v4, v16, 16, 1
	v_add3_u32 v4, v16, v4, s45
	s_waitcnt lgkmcnt(2)
	v_bfe_u32 v9, v30, 16, 1
	ds_read2_b32 v[36:37], v22 offset0:132 offset1:140
	v_mov_b32_e32 v11, v5
	v_lshrrev_b32_e32 v4, 16, v4
	v_add3_u32 v9, v30, v9, s45
	ds_read2_b32 v[38:39], v22 offset0:165 offset1:173
	v_lshl_add_u64 v[18:19], v[12:13], 0, v[10:11]
	v_and_or_b32 v12, v9, s46, v4
	s_waitcnt lgkmcnt(3)
	v_bfe_u32 v4, v32, 16, 1
	v_add3_u32 v4, v32, v4, s45
	s_waitcnt lgkmcnt(2)
	v_bfe_u32 v9, v34, 16, 1
	ds_read2_b32 v[40:41], v22 offset0:198 offset1:206
	v_lshrrev_b32_e32 v4, 16, v4
	v_add3_u32 v9, v34, v9, s45
	ds_read2_b32 v[42:43], v22 offset0:231 offset1:239
	v_and_or_b32 v13, v9, s46, v4
	s_waitcnt lgkmcnt(3)
	v_bfe_u32 v4, v36, 16, 1
	v_add3_u32 v4, v36, v4, s45
	s_waitcnt lgkmcnt(2)
	v_bfe_u32 v9, v38, 16, 1
	v_lshrrev_b32_e32 v4, 16, v4
	v_add3_u32 v9, v38, v9, s45
	v_and_or_b32 v14, v9, s46, v4
	s_waitcnt lgkmcnt(1)
	v_bfe_u32 v4, v40, 16, 1
	v_add3_u32 v4, v40, v4, s45
	s_waitcnt lgkmcnt(0)
	v_bfe_u32 v9, v42, 16, 1
	v_lshrrev_b32_e32 v4, 16, v4
	v_add3_u32 v9, v42, v9, s45
	v_and_or_b32 v15, v9, s46, v4
	v_or_b32_e32 v4, v3, v21
	v_lshlrev_b32_e32 v4, 12, v4
	v_lshl_add_u64 v[44:45], v[18:19], 0, v[4:5]
	v_bfe_u32 v4, v17, 16, 1
	v_add3_u32 v4, v17, v4, s45
	v_bfe_u32 v9, v31, 16, 1
	v_lshrrev_b32_e32 v4, 16, v4
	v_add3_u32 v9, v31, v9, s45
	global_store_dwordx4 v[44:45], v[12:15], off nt
	ds_read2_b32 v[16:17], v22 offset0:16 offset1:24
	v_readlane_b32 s66, v253, 1
	v_and_or_b32 v12, v9, s46, v4
	v_bfe_u32 v4, v33, 16, 1
	v_add3_u32 v4, v33, v4, s45
	v_bfe_u32 v9, v35, 16, 1
	v_lshrrev_b32_e32 v4, 16, v4
	v_add3_u32 v9, v35, v9, s45
	v_and_or_b32 v13, v9, s46, v4
	v_bfe_u32 v4, v37, 16, 1
	v_add3_u32 v4, v37, v4, s45
	v_bfe_u32 v9, v39, 16, 1
	v_lshrrev_b32_e32 v4, 16, v4
	v_add3_u32 v9, v39, v9, s45
	v_and_or_b32 v14, v9, s46, v4
	v_bfe_u32 v4, v41, 16, 1
	v_add3_u32 v4, v41, v4, s45
	v_bfe_u32 v9, v43, 16, 1
	v_lshrrev_b32_e32 v4, 16, v4
	v_add3_u32 v9, v43, v9, s45
	v_and_or_b32 v15, v9, s46, v4
	v_or_b32_e32 v4, v3, v23
	v_lshlrev_b32_e32 v4, 12, v4
	v_lshl_add_u64 v[30:31], v[18:19], 0, v[4:5]
	global_store_dwordx4 v[30:31], v[12:15], off nt
	ds_read2_b32 v[30:31], v22 offset0:49 offset1:57
	ds_read2_b32 v[32:33], v22 offset0:82 offset1:90
	ds_read2_b32 v[34:35], v22 offset0:115 offset1:123
	s_waitcnt lgkmcnt(3)
	v_bfe_u32 v4, v16, 16, 1
	v_add3_u32 v4, v16, v4, s45
	s_waitcnt lgkmcnt(2)
	v_bfe_u32 v9, v30, 16, 1
	ds_read2_b32 v[36:37], v22 offset0:148 offset1:156
	v_lshrrev_b32_e32 v4, 16, v4
	v_add3_u32 v9, v30, v9, s45
	ds_read2_b32 v[38:39], v22 offset0:181 offset1:189
	v_and_or_b32 v12, v9, s46, v4
	s_waitcnt lgkmcnt(3)
	v_bfe_u32 v4, v32, 16, 1
	v_add3_u32 v4, v32, v4, s45
	s_waitcnt lgkmcnt(2)
	v_bfe_u32 v9, v34, 16, 1
	ds_read2_b32 v[40:41], v22 offset0:214 offset1:222
	v_lshrrev_b32_e32 v4, 16, v4
	v_add3_u32 v9, v34, v9, s45
	ds_read2_b32 v[42:43], v22 offset0:247 offset1:255
	v_and_or_b32 v13, v9, s46, v4
	s_waitcnt lgkmcnt(3)
	v_bfe_u32 v4, v36, 16, 1
	v_add3_u32 v4, v36, v4, s45
	s_waitcnt lgkmcnt(2)
	v_bfe_u32 v9, v38, 16, 1
	v_lshrrev_b32_e32 v4, 16, v4
	v_add3_u32 v9, v38, v9, s45
	v_and_or_b32 v14, v9, s46, v4
	s_waitcnt lgkmcnt(1)
	v_bfe_u32 v4, v40, 16, 1
	v_add3_u32 v4, v40, v4, s45
	s_waitcnt lgkmcnt(0)
	v_bfe_u32 v9, v42, 16, 1
	v_lshrrev_b32_e32 v4, 16, v4
	v_add3_u32 v9, v42, v9, s45
	v_and_or_b32 v15, v9, s46, v4
	v_or_b32_e32 v4, v3, v24
	v_lshlrev_b32_e32 v4, 12, v4
	v_lshl_add_u64 v[44:45], v[18:19], 0, v[4:5]
	v_bfe_u32 v4, v17, 16, 1
	v_add3_u32 v4, v17, v4, s45
	v_bfe_u32 v9, v31, 16, 1
	v_lshrrev_b32_e32 v4, 16, v4
	v_add3_u32 v9, v31, v9, s45
	global_store_dwordx4 v[44:45], v[12:15], off nt
	v_or_b32_e32 v3, v3, v25
	s_nop 0
	v_and_or_b32 v12, v9, s46, v4
	v_bfe_u32 v4, v33, 16, 1
	v_add3_u32 v4, v33, v4, s45
	v_bfe_u32 v9, v35, 16, 1
	v_lshrrev_b32_e32 v4, 16, v4
	v_add3_u32 v9, v35, v9, s45
	v_and_or_b32 v13, v9, s46, v4
	v_bfe_u32 v4, v37, 16, 1
	v_add3_u32 v4, v37, v4, s45
	v_bfe_u32 v9, v39, 16, 1
	v_lshrrev_b32_e32 v4, 16, v4
	v_add3_u32 v9, v39, v9, s45
	v_and_or_b32 v14, v9, s46, v4
	v_bfe_u32 v4, v41, 16, 1
	v_add3_u32 v4, v41, v4, s45
	v_bfe_u32 v9, v43, 16, 1
	v_lshrrev_b32_e32 v4, 16, v4
	v_add3_u32 v9, v43, v9, s45
	v_and_or_b32 v15, v9, s46, v4
	v_lshlrev_b32_e32 v4, 12, v3
	v_lshl_add_u64 v[16:17], v[18:19], 0, v[4:5]
	global_store_dwordx4 v[16:17], v[12:15], off nt
	s_waitcnt lgkmcnt(0)

.LBB0_135:
	s_andn2_saveexec_b64 s[26:27], s[26:27]
	s_cbranch_execz .LBB0_139
	s_load_dwordx2 s[28:29], s[6:7], 0x78
	v_and_b32_e32 v4, 0x1fc0, v3
	v_ashrrev_i32_e32 v13, 31, v12
	v_lshlrev_b32_e32 v3, 5, v3
	v_lshlrev_b64 v[16:17], 22, v[12:13]
	v_lshlrev_b64 v[12:13], 24, v[12:13]
	v_and_b32_e32 v18, 0x7e0, v3
	v_add_u32_e32 v14, 0xffffefc0, v4
	s_waitcnt lgkmcnt(0)
	v_lshl_add_u64 v[12:13], s[28:29], 0, v[12:13]
	v_lshlrev_b32_e32 v4, 2, v18
	v_lshl_add_u64 v[12:13], v[12:13], 0, v[4:5]
	v_mov_b32_e32 v9, v5
	v_lshl_add_u64 v[12:13], v[12:13], 0, v[8:9]
	v_mov_b32_e32 v3, v14
	s_mov_b32 s28, 1
	s_mov_b32 s29, 0
	s_mov_b32 s30, 32
	s_lshl_b32 s31, s28, 1
	s_lshl_b32 s34, s29, 1
	v_or_b32_e32 v104, s31, v1
	v_or_b32_e32 v109, s34, v2
	s_add_i32 s35, s31, 4
	s_add_i32 s36, s34, 4
	s_add_i32 s37, s31, 8
	s_add_i32 s58, s34, 8
	s_add_i32 s59, s31, 12
	s_add_i32 s60, s34, 12
	s_add_i32 s61, s31, 16
	s_add_i32 s62, s34, 16
	s_add_i32 s63, s31, 20
	s_add_i32 s64, s34, 20
	s_add_i32 s65, s31, 24
	s_add_i32 s66, s34, 24
	s_add_i32 s31, s31, 28
	s_add_i32 s34, s34, 28
	v_add_u32_e32 v132, v109, v14
	v_or_b32_e32 v111, s35, v1
	v_or_b32_e32 v115, s36, v2
	v_or_b32_e32 v119, s37, v1
	v_or_b32_e32 v129, s58, v2
	v_or_b32_e32 v162, s59, v1
	v_or_b32_e32 v163, s60, v2
	v_or_b32_e32 v164, s61, v1
	v_or_b32_e32 v165, s62, v2
	v_or_b32_e32 v166, s63, v1
	v_or_b32_e32 v167, s64, v2
	v_or_b32_e32 v168, s65, v1
	v_or_b32_e32 v169, s66, v2
	v_or_b32_e32 v170, s31, v1
	v_or_b32_e32 v171, s34, v2
	v_add_u32_e32 v130, v104, v3
	v_ashrrev_i32_e32 v133, 31, v132
	v_add_u32_e32 v134, v111, v3
	v_add_u32_e32 v136, v115, v14
	v_add_u32_e32 v138, v119, v3
	v_add_u32_e32 v140, v129, v14
	v_add_u32_e32 v142, v162, v3
	v_add_u32_e32 v144, v163, v14
	v_add_u32_e32 v146, v164, v3
	v_add_u32_e32 v148, v165, v14
	v_add_u32_e32 v150, v166, v3
	v_add_u32_e32 v152, v167, v14
	v_add_u32_e32 v154, v168, v3
	v_add_u32_e32 v156, v169, v14
	v_add_u32_e32 v158, v170, v3
	v_add_u32_e32 v160, v171, v14
	v_ashrrev_i32_e32 v131, 31, v130
	v_lshlrev_b64 v[132:133], 13, v[132:133]
	v_ashrrev_i32_e32 v137, 31, v136
	v_ashrrev_i32_e32 v135, 31, v134
	v_ashrrev_i32_e32 v141, 31, v140
	v_ashrrev_i32_e32 v139, 31, v138
	v_ashrrev_i32_e32 v145, 31, v144
	v_ashrrev_i32_e32 v143, 31, v142
	v_ashrrev_i32_e32 v149, 31, v148
	v_ashrrev_i32_e32 v147, 31, v146
	v_ashrrev_i32_e32 v153, 31, v152
	v_ashrrev_i32_e32 v151, 31, v150
	v_ashrrev_i32_e32 v157, 31, v156
	v_ashrrev_i32_e32 v155, 31, v154
	v_ashrrev_i32_e32 v161, 31, v160
	v_ashrrev_i32_e32 v159, 31, v158
	v_lshlrev_b64 v[130:131], 13, v[130:131]
	v_lshl_add_u64 v[132:133], v[12:13], 0, v[132:133]
	v_lshlrev_b64 v[134:135], 13, v[134:135]
	v_lshlrev_b64 v[136:137], 13, v[136:137]
	v_lshlrev_b64 v[138:139], 13, v[138:139]
	v_lshlrev_b64 v[140:141], 13, v[140:141]
	v_lshlrev_b64 v[142:143], 13, v[142:143]
	v_lshlrev_b64 v[144:145], 13, v[144:145]
	v_lshlrev_b64 v[146:147], 13, v[146:147]
	v_lshlrev_b64 v[148:149], 13, v[148:149]
	v_lshlrev_b64 v[150:151], 13, v[150:151]
	v_lshlrev_b64 v[152:153], 13, v[152:153]
	v_lshlrev_b64 v[154:155], 13, v[154:155]
	v_lshlrev_b64 v[156:157], 13, v[156:157]
	v_lshlrev_b64 v[158:159], 13, v[158:159]
	v_lshlrev_b64 v[160:161], 13, v[160:161]
	v_lshl_add_u64 v[130:131], v[12:13], 0, v[130:131]
	v_lshl_add_u64 v[136:137], v[12:13], 0, v[136:137]
	v_lshl_add_u64 v[134:135], v[12:13], 0, v[134:135]
	v_lshl_add_u64 v[140:141], v[12:13], 0, v[140:141]
	v_lshl_add_u64 v[138:139], v[12:13], 0, v[138:139]
	v_lshl_add_u64 v[144:145], v[12:13], 0, v[144:145]
	v_lshl_add_u64 v[142:143], v[12:13], 0, v[142:143]
	v_lshl_add_u64 v[148:149], v[12:13], 0, v[148:149]
	v_lshl_add_u64 v[146:147], v[12:13], 0, v[146:147]
	v_lshl_add_u64 v[152:153], v[12:13], 0, v[152:153]
	v_lshl_add_u64 v[150:151], v[12:13], 0, v[150:151]
	v_lshl_add_u64 v[156:157], v[12:13], 0, v[156:157]
	v_lshl_add_u64 v[154:155], v[12:13], 0, v[154:155]
	v_lshl_add_u64 v[160:161], v[12:13], 0, v[160:161]
	v_lshl_add_u64 v[158:159], v[12:13], 0, v[158:159]
	global_load_dword v172, v[132:133], off nt
	global_load_dword v173, v[130:131], off nt
	global_load_dword v174, v[136:137], off nt
	global_load_dword v175, v[134:135], off nt
	global_load_dword v176, v[140:141], off nt
	global_load_dword v177, v[138:139], off nt
	global_load_dword v178, v[144:145], off nt
	global_load_dword v179, v[142:143], off nt
	global_load_dword v180, v[148:149], off nt
	global_load_dword v181, v[146:147], off nt
	global_load_dword v182, v[152:153], off nt
	global_load_dword v183, v[150:151], off nt
	global_load_dword v184, v[156:157], off nt
	global_load_dword v185, v[154:155], off nt
	global_load_dword v186, v[160:161], off nt
	global_load_dword v187, v[158:159], off nt
	s_add_i32 s29, s29, 16
	s_add_i32 s28, s28, 16
	s_add_i32 s30, s30, -16
	v_mad_u64_u32 v[130:131], s[34:35], v109, s33, v[6:7]
	v_mad_u64_u32 v[132:133], s[34:35], v104, s33, v[6:7]
	v_mad_u64_u32 v[134:135], s[34:35], v115, s33, v[6:7]
	v_mad_u64_u32 v[136:137], s[34:35], v111, s33, v[6:7]
	v_mad_u64_u32 v[138:139], s[34:35], v129, s33, v[6:7]
	v_mad_u64_u32 v[140:141], s[34:35], v119, s33, v[6:7]
	v_mad_u64_u32 v[142:143], s[34:35], v163, s33, v[6:7]
	v_mad_u64_u32 v[144:145], s[34:35], v162, s33, v[6:7]
	v_mad_u64_u32 v[146:147], s[34:35], v165, s33, v[6:7]
	v_mad_u64_u32 v[148:149], s[34:35], v164, s33, v[6:7]
	v_mad_u64_u32 v[150:151], s[34:35], v167, s33, v[6:7]
	v_mad_u64_u32 v[152:153], s[34:35], v166, s33, v[6:7]
	v_mad_u64_u32 v[154:155], s[34:35], v169, s33, v[6:7]
	v_mad_u64_u32 v[156:157], s[34:35], v168, s33, v[6:7]
	v_mad_u64_u32 v[158:159], s[34:35], v171, s33, v[6:7]
	v_mad_u64_u32 v[160:161], s[34:35], v170, s33, v[6:7]
	s_lshl_b32 s31, s28, 1
	s_lshl_b32 s34, s29, 1
	v_or_b32_e32 v4, s31, v1
	v_or_b32_e32 v9, s34, v2
	s_add_i32 s35, s31, 4
	s_add_i32 s36, s34, 4
	s_add_i32 s37, s31, 8
	s_add_i32 s58, s34, 8
	s_add_i32 s59, s31, 12
	s_add_i32 s60, s34, 12
	s_add_i32 s61, s31, 16
	s_add_i32 s62, s34, 16
	s_add_i32 s63, s31, 20
	s_add_i32 s64, s34, 20
	s_add_i32 s65, s31, 24
	s_add_i32 s66, s34, 24
	s_add_i32 s31, s31, 28
	s_add_i32 s34, s34, 28
	v_add_u32_e32 v32, v9, v14
	v_or_b32_e32 v11, s35, v1
	v_or_b32_e32 v15, s36, v2
	v_or_b32_e32 v19, s37, v1
	v_or_b32_e32 v29, s58, v2
	v_or_b32_e32 v62, s59, v1
	v_or_b32_e32 v63, s60, v2
	v_or_b32_e32 v64, s61, v1
	v_or_b32_e32 v65, s62, v2
	v_or_b32_e32 v66, s63, v1
	v_or_b32_e32 v67, s64, v2
	v_or_b32_e32 v68, s65, v1
	v_or_b32_e32 v69, s66, v2
	v_or_b32_e32 v70, s31, v1
	v_or_b32_e32 v71, s34, v2
	v_add_u32_e32 v30, v4, v3
	v_ashrrev_i32_e32 v33, 31, v32
	v_add_u32_e32 v34, v11, v3
	v_add_u32_e32 v36, v15, v14
	v_add_u32_e32 v38, v19, v3
	v_add_u32_e32 v40, v29, v14
	v_add_u32_e32 v42, v62, v3
	v_add_u32_e32 v44, v63, v14
	v_add_u32_e32 v46, v64, v3
	v_add_u32_e32 v48, v65, v14
	v_add_u32_e32 v50, v66, v3
	v_add_u32_e32 v52, v67, v14
	v_add_u32_e32 v54, v68, v3
	v_add_u32_e32 v56, v69, v14
	v_add_u32_e32 v58, v70, v3
	v_add_u32_e32 v60, v71, v14
	v_ashrrev_i32_e32 v31, 31, v30
	v_lshlrev_b64 v[32:33], 13, v[32:33]
	v_ashrrev_i32_e32 v37, 31, v36
	v_ashrrev_i32_e32 v35, 31, v34
	v_ashrrev_i32_e32 v41, 31, v40
	v_ashrrev_i32_e32 v39, 31, v38
	v_ashrrev_i32_e32 v45, 31, v44
	v_ashrrev_i32_e32 v43, 31, v42
	v_ashrrev_i32_e32 v49, 31, v48
	v_ashrrev_i32_e32 v47, 31, v46
	v_ashrrev_i32_e32 v53, 31, v52
	v_ashrrev_i32_e32 v51, 31, v50
	v_ashrrev_i32_e32 v57, 31, v56
	v_ashrrev_i32_e32 v55, 31, v54
	v_ashrrev_i32_e32 v61, 31, v60
	v_ashrrev_i32_e32 v59, 31, v58
	v_lshlrev_b64 v[30:31], 13, v[30:31]
	v_lshl_add_u64 v[32:33], v[12:13], 0, v[32:33]
	v_lshlrev_b64 v[34:35], 13, v[34:35]
	v_lshlrev_b64 v[36:37], 13, v[36:37]
	v_lshlrev_b64 v[38:39], 13, v[38:39]
	v_lshlrev_b64 v[40:41], 13, v[40:41]
	v_lshlrev_b64 v[42:43], 13, v[42:43]
	v_lshlrev_b64 v[44:45], 13, v[44:45]
	v_lshlrev_b64 v[46:47], 13, v[46:47]
	v_lshlrev_b64 v[48:49], 13, v[48:49]
	v_lshlrev_b64 v[50:51], 13, v[50:51]
	v_lshlrev_b64 v[52:53], 13, v[52:53]
	v_lshlrev_b64 v[54:55], 13, v[54:55]
	v_lshlrev_b64 v[56:57], 13, v[56:57]
	v_lshlrev_b64 v[58:59], 13, v[58:59]
	v_lshlrev_b64 v[60:61], 13, v[60:61]
	v_lshl_add_u64 v[30:31], v[12:13], 0, v[30:31]
	v_lshl_add_u64 v[36:37], v[12:13], 0, v[36:37]
	v_lshl_add_u64 v[34:35], v[12:13], 0, v[34:35]
	v_lshl_add_u64 v[40:41], v[12:13], 0, v[40:41]
	v_lshl_add_u64 v[38:39], v[12:13], 0, v[38:39]
	v_lshl_add_u64 v[44:45], v[12:13], 0, v[44:45]
	v_lshl_add_u64 v[42:43], v[12:13], 0, v[42:43]
	v_lshl_add_u64 v[48:49], v[12:13], 0, v[48:49]
	v_lshl_add_u64 v[46:47], v[12:13], 0, v[46:47]
	v_lshl_add_u64 v[52:53], v[12:13], 0, v[52:53]
	v_lshl_add_u64 v[50:51], v[12:13], 0, v[50:51]
	v_lshl_add_u64 v[56:57], v[12:13], 0, v[56:57]
	v_lshl_add_u64 v[54:55], v[12:13], 0, v[54:55]
	v_lshl_add_u64 v[60:61], v[12:13], 0, v[60:61]
	v_lshl_add_u64 v[58:59], v[12:13], 0, v[58:59]
	global_load_dword v72, v[32:33], off nt
	global_load_dword v73, v[30:31], off nt
	global_load_dword v74, v[36:37], off nt
	global_load_dword v75, v[34:35], off nt
	global_load_dword v76, v[40:41], off nt
	global_load_dword v77, v[38:39], off nt
	global_load_dword v78, v[44:45], off nt
	global_load_dword v79, v[42:43], off nt
	global_load_dword v80, v[48:49], off nt
	global_load_dword v81, v[46:47], off nt
	global_load_dword v82, v[52:53], off nt
	global_load_dword v83, v[50:51], off nt
	global_load_dword v84, v[56:57], off nt
	global_load_dword v85, v[54:55], off nt
	global_load_dword v86, v[60:61], off nt
	global_load_dword v87, v[58:59], off nt
	s_add_i32 s29, s29, 16
	s_add_i32 s28, s28, 16
	s_add_i32 s30, s30, -16
	v_mad_u64_u32 v[30:31], s[34:35], v9, s33, v[6:7]
	v_mad_u64_u32 v[32:33], s[34:35], v4, s33, v[6:7]
	v_mad_u64_u32 v[34:35], s[34:35], v15, s33, v[6:7]
	v_mad_u64_u32 v[36:37], s[34:35], v11, s33, v[6:7]
	v_mad_u64_u32 v[38:39], s[34:35], v29, s33, v[6:7]
	v_mad_u64_u32 v[40:41], s[34:35], v19, s33, v[6:7]
	v_mad_u64_u32 v[42:43], s[34:35], v63, s33, v[6:7]
	v_mad_u64_u32 v[44:45], s[34:35], v62, s33, v[6:7]
	v_mad_u64_u32 v[46:47], s[34:35], v65, s33, v[6:7]
	v_mad_u64_u32 v[48:49], s[34:35], v64, s33, v[6:7]
	v_mad_u64_u32 v[50:51], s[34:35], v67, s33, v[6:7]
	v_mad_u64_u32 v[52:53], s[34:35], v66, s33, v[6:7]
	v_mad_u64_u32 v[54:55], s[34:35], v69, s33, v[6:7]
	v_mad_u64_u32 v[56:57], s[34:35], v68, s33, v[6:7]
	v_mad_u64_u32 v[58:59], s[34:35], v71, s33, v[6:7]
	v_mad_u64_u32 v[60:61], s[34:35], v70, s33, v[6:7]
	s_waitcnt vmcnt(31)
	ds_write_b32 v130, v172
	s_waitcnt vmcnt(30)
	ds_write_b32 v132, v173
	s_waitcnt vmcnt(29)
	ds_write_b32 v134, v174
	s_waitcnt vmcnt(28)
	ds_write_b32 v136, v175
	s_waitcnt vmcnt(27)
	ds_write_b32 v138, v176
	s_waitcnt vmcnt(26)
	ds_write_b32 v140, v177
	s_waitcnt vmcnt(25)
	ds_write_b32 v142, v178
	s_waitcnt vmcnt(24)
	ds_write_b32 v144, v179
	s_waitcnt vmcnt(23)
	ds_write_b32 v146, v180
	s_waitcnt vmcnt(22)
	ds_write_b32 v148, v181
	s_waitcnt vmcnt(21)
	ds_write_b32 v150, v182
	s_waitcnt vmcnt(20)
	ds_write_b32 v152, v183
	s_waitcnt vmcnt(19)
	ds_write_b32 v154, v184
	s_waitcnt vmcnt(18)
	ds_write_b32 v156, v185
	s_waitcnt vmcnt(17)
	ds_write_b32 v158, v186
	s_waitcnt vmcnt(16)
	ds_write_b32 v160, v187
	s_waitcnt vmcnt(15)
	ds_write_b32 v30, v72
	s_waitcnt vmcnt(14)
	ds_write_b32 v32, v73
	s_waitcnt vmcnt(13)
	ds_write_b32 v34, v74
	s_waitcnt vmcnt(12)
	ds_write_b32 v36, v75
	s_waitcnt vmcnt(11)
	ds_write_b32 v38, v76
	s_waitcnt vmcnt(10)
	ds_write_b32 v40, v77
	s_waitcnt vmcnt(9)
	ds_write_b32 v42, v78
	s_waitcnt vmcnt(8)
	ds_write_b32 v44, v79
	s_waitcnt vmcnt(7)
	ds_write_b32 v46, v80
	s_waitcnt vmcnt(6)
	ds_write_b32 v48, v81
	s_waitcnt vmcnt(5)
	ds_write_b32 v50, v82
	s_waitcnt vmcnt(4)
	ds_write_b32 v52, v83
	s_waitcnt vmcnt(3)
	ds_write_b32 v54, v84
	s_waitcnt vmcnt(2)
	ds_write_b32 v56, v85
	s_waitcnt vmcnt(1)
	ds_write_b32 v58, v86
	s_waitcnt vmcnt(0)
	ds_write_b32 v60, v87
	s_waitcnt lgkmcnt(0)
	v_lshl_add_u64 v[12:13], v[16:17], 1, s[16:17]
	ds_read2_b32 v[16:17], v22 offset1:8
	ds_read2_b32 v[32:33], v22 offset0:33 offset1:41
	ds_read2_b32 v[34:35], v22 offset0:66 offset1:74
	ds_read2_b32 v[36:37], v22 offset0:99 offset1:107
	v_mov_b32_e32 v15, v5
	s_waitcnt lgkmcnt(3)
	v_bfe_u32 v3, v16, 16, 1
	v_add3_u32 v3, v16, v3, s45
	s_waitcnt lgkmcnt(2)
	v_bfe_u32 v4, v32, 16, 1
	ds_read2_b32 v[38:39], v22 offset0:132 offset1:140
	v_lshl_add_u64 v[12:13], v[14:15], 1, v[12:13]
	v_mov_b32_e32 v11, v5
	v_lshrrev_b32_e32 v3, 16, v3
	v_add3_u32 v4, v32, v4, s45
	ds_read2_b32 v[40:41], v22 offset0:165 offset1:173
	v_lshl_add_u64 v[30:31], v[12:13], 0, v[10:11]
	v_and_or_b32 v12, v4, s46, v3
	s_waitcnt lgkmcnt(3)
	v_bfe_u32 v3, v34, 16, 1
	v_add3_u32 v3, v34, v3, s45
	s_waitcnt lgkmcnt(2)
	v_bfe_u32 v4, v36, 16, 1
	ds_read2_b32 v[42:43], v22 offset0:198 offset1:206
	v_lshrrev_b32_e32 v3, 16, v3
	v_add3_u32 v4, v36, v4, s45
	ds_read2_b32 v[44:45], v22 offset0:231 offset1:239
	v_and_or_b32 v13, v4, s46, v3
	s_waitcnt lgkmcnt(3)
	v_bfe_u32 v3, v38, 16, 1
	v_add3_u32 v3, v38, v3, s45
	s_waitcnt lgkmcnt(2)
	v_bfe_u32 v4, v40, 16, 1
	v_lshrrev_b32_e32 v3, 16, v3
	v_add3_u32 v4, v40, v4, s45
	v_and_or_b32 v14, v4, s46, v3
	s_waitcnt lgkmcnt(1)
	v_bfe_u32 v3, v42, 16, 1
	v_add3_u32 v3, v42, v3, s45
	s_waitcnt lgkmcnt(0)
	v_bfe_u32 v4, v44, 16, 1
	v_lshrrev_b32_e32 v3, 16, v3
	v_add3_u32 v4, v44, v4, s45
	v_and_or_b32 v15, v4, s46, v3
	v_or_b32_e32 v3, v18, v21
	v_lshlrev_b32_e32 v4, 12, v3
	v_bfe_u32 v3, v17, 16, 1
	v_lshl_add_u64 v[46:47], v[30:31], 0, v[4:5]
	v_add3_u32 v3, v17, v3, s45
	v_bfe_u32 v4, v33, 16, 1
	v_lshrrev_b32_e32 v3, 16, v3
	v_add3_u32 v4, v33, v4, s45
	global_store_dwordx4 v[46:47], v[12:15], off nt
	ds_read2_b32 v[16:17], v22 offset0:16 offset1:24
	v_readlane_b32 s66, v253, 1
	v_and_or_b32 v12, v4, s46, v3
	v_bfe_u32 v3, v35, 16, 1
	v_add3_u32 v3, v35, v3, s45
	v_bfe_u32 v4, v37, 16, 1
	v_lshrrev_b32_e32 v3, 16, v3
	v_add3_u32 v4, v37, v4, s45
	v_and_or_b32 v13, v4, s46, v3
	v_bfe_u32 v3, v39, 16, 1
	v_add3_u32 v3, v39, v3, s45
	v_bfe_u32 v4, v41, 16, 1
	v_lshrrev_b32_e32 v3, 16, v3
	v_add3_u32 v4, v41, v4, s45
	v_and_or_b32 v14, v4, s46, v3
	v_bfe_u32 v3, v43, 16, 1
	v_add3_u32 v3, v43, v3, s45
	v_bfe_u32 v4, v45, 16, 1
	v_lshrrev_b32_e32 v3, 16, v3
	v_add3_u32 v4, v45, v4, s45
	v_and_or_b32 v15, v4, s46, v3
	v_or_b32_e32 v3, v18, v23
	v_lshlrev_b32_e32 v4, 12, v3
	v_lshl_add_u64 v[32:33], v[30:31], 0, v[4:5]
	global_store_dwordx4 v[32:33], v[12:15], off nt
	ds_read2_b32 v[32:33], v22 offset0:49 offset1:57
	ds_read2_b32 v[34:35], v22 offset0:82 offset1:90
	ds_read2_b32 v[36:37], v22 offset0:115 offset1:123
	s_waitcnt lgkmcnt(3)
	v_bfe_u32 v3, v16, 16, 1
	v_add3_u32 v3, v16, v3, s45
	s_waitcnt lgkmcnt(2)
	v_bfe_u32 v4, v32, 16, 1
	ds_read2_b32 v[38:39], v22 offset0:148 offset1:156
	v_lshrrev_b32_e32 v3, 16, v3
	v_add3_u32 v4, v32, v4, s45
	ds_read2_b32 v[40:41], v22 offset0:181 offset1:189
	v_and_or_b32 v12, v4, s46, v3
	s_waitcnt lgkmcnt(3)
	v_bfe_u32 v3, v34, 16, 1
	v_add3_u32 v3, v34, v3, s45
	s_waitcnt lgkmcnt(2)
	v_bfe_u32 v4, v36, 16, 1
	ds_read2_b32 v[42:43], v22 offset0:214 offset1:222
	v_lshrrev_b32_e32 v3, 16, v3
	v_add3_u32 v4, v36, v4, s45
	ds_read2_b32 v[44:45], v22 offset0:247 offset1:255
	v_and_or_b32 v13, v4, s46, v3
	s_waitcnt lgkmcnt(3)
	v_bfe_u32 v3, v38, 16, 1
	v_add3_u32 v3, v38, v3, s45
	s_waitcnt lgkmcnt(2)
	v_bfe_u32 v4, v40, 16, 1
	v_lshrrev_b32_e32 v3, 16, v3
	v_add3_u32 v4, v40, v4, s45
	v_and_or_b32 v14, v4, s46, v3
	s_waitcnt lgkmcnt(1)
	v_bfe_u32 v3, v42, 16, 1
	v_add3_u32 v3, v42, v3, s45
	s_waitcnt lgkmcnt(0)
	v_bfe_u32 v4, v44, 16, 1
	v_lshrrev_b32_e32 v3, 16, v3
	v_add3_u32 v4, v44, v4, s45
	v_and_or_b32 v15, v4, s46, v3
	v_or_b32_e32 v3, v18, v24
	v_lshlrev_b32_e32 v4, 12, v3
	v_bfe_u32 v3, v17, 16, 1
	v_lshl_add_u64 v[46:47], v[30:31], 0, v[4:5]
	v_add3_u32 v3, v17, v3, s45
	v_bfe_u32 v4, v33, 16, 1
	v_lshrrev_b32_e32 v3, 16, v3
	v_add3_u32 v4, v33, v4, s45
	global_store_dwordx4 v[46:47], v[12:15], off nt
	s_nop 1
	v_and_or_b32 v12, v4, s46, v3
	v_bfe_u32 v3, v35, 16, 1
	v_add3_u32 v3, v35, v3, s45
	v_bfe_u32 v4, v37, 16, 1
	v_lshrrev_b32_e32 v3, 16, v3
	v_add3_u32 v4, v37, v4, s45
	v_and_or_b32 v13, v4, s46, v3
	v_bfe_u32 v3, v39, 16, 1
	v_add3_u32 v3, v39, v3, s45
	v_bfe_u32 v4, v41, 16, 1
	v_lshrrev_b32_e32 v3, 16, v3
	v_add3_u32 v4, v41, v4, s45
	v_and_or_b32 v14, v4, s46, v3
	v_bfe_u32 v3, v43, 16, 1
	v_add3_u32 v3, v43, v3, s45
	v_bfe_u32 v4, v45, 16, 1
	v_lshrrev_b32_e32 v3, 16, v3
	v_add3_u32 v4, v45, v4, s45
	v_and_or_b32 v15, v4, s46, v3
	v_or_b32_e32 v3, v18, v25
	v_lshlrev_b32_e32 v4, 12, v3
	v_lshl_add_u64 v[16:17], v[30:31], 0, v[4:5]
	global_store_dwordx4 v[16:17], v[12:15], off nt
	s_waitcnt lgkmcnt(0)

.LBB0_140:
	s_andn2_saveexec_b64 s[24:25], s[24:25]
	s_cbranch_execz .LBB0_105
	s_load_dwordx2 s[26:27], s[6:7], 0x30
	v_mul_i32_i24_e32 v4, 0xfc1, v3
	v_lshrrev_b32_e32 v9, 31, v4
	v_ashrrev_i32_e32 v4, 19, v4
	v_add_u16_e32 v4, v4, v9
	v_mul_lo_u16_e32 v9, 0x82, v4
	v_sub_u16_e32 v3, v3, v9
	s_waitcnt lgkmcnt(0)
	v_mov_b64_e32 v[14:15], s[26:27]
	v_mad_i64_i32 v[18:19], s[26:27], v12, s54, v[14:15]
	v_lshlrev_b32_sdwa v14, v26, sext(v3) dst_sel:DWORD dst_unused:UNUSED_PAD src0_sel:DWORD src1_sel:WORD_0
	v_ashrrev_i32_e32 v15, 31, v14
	v_lshlrev_b32_sdwa v16, v28, sext(v4) dst_sel:DWORD dst_unused:UNUSED_PAD src0_sel:DWORD src1_sel:WORD_0
	v_lshl_add_u64 v[18:19], v[14:15], 2, v[18:19]
	v_mov_b32_e32 v9, v5
	v_lshl_add_u64 v[18:19], v[18:19], 0, v[8:9]
	v_mov_b32_e32 v3, v16
	s_mov_b32 s26, 1
	s_mov_b32 s27, 0
	s_mov_b32 s28, 32
	s_lshl_b32 s29, s26, 1
	s_lshl_b32 s30, s27, 1
	v_or_b32_e32 v104, s29, v1
	v_or_b32_e32 v109, s30, v2
	s_add_i32 s31, s29, 4
	s_add_i32 s34, s30, 4
	s_add_i32 s35, s29, 8
	s_add_i32 s36, s30, 8
	s_add_i32 s37, s29, 12
	s_add_i32 s58, s30, 12
	s_add_i32 s59, s29, 16
	s_add_i32 s60, s30, 16
	s_add_i32 s61, s29, 20
	s_add_i32 s62, s30, 20
	s_add_i32 s63, s29, 24
	s_add_i32 s64, s30, 24
	s_add_i32 s29, s29, 28
	s_add_i32 s30, s30, 28
	v_add_u32_e32 v111, v104, v3
	v_add_u32_e32 v113, v109, v16
	v_or_b32_e32 v115, s31, v1
	v_or_b32_e32 v117, s34, v2
	v_or_b32_e32 v129, s35, v1
	v_or_b32_e32 v162, s36, v2
	v_or_b32_e32 v163, s37, v1
	v_or_b32_e32 v164, s58, v2
	v_or_b32_e32 v165, s59, v1
	v_or_b32_e32 v166, s60, v2
	v_or_b32_e32 v167, s61, v1
	v_or_b32_e32 v168, s62, v2
	v_or_b32_e32 v169, s63, v1
	v_or_b32_e32 v170, s64, v2
	v_or_b32_e32 v171, s29, v1
	v_or_b32_e32 v172, s30, v2
	v_mad_i64_i32 v[130:131], s[30:31], v113, s55, v[18:19]
	v_mad_i64_i32 v[132:133], s[30:31], v111, s55, v[18:19]
	v_add_u32_e32 v111, v115, v3
	v_add_u32_e32 v113, v117, v16
	v_add_u32_e32 v140, v129, v3
	v_add_u32_e32 v138, v162, v16
	v_add_u32_e32 v144, v163, v3
	v_add_u32_e32 v142, v164, v16
	v_add_u32_e32 v148, v165, v3
	v_add_u32_e32 v146, v166, v16
	v_add_u32_e32 v152, v167, v3
	v_add_u32_e32 v150, v168, v16
	v_add_u32_e32 v156, v169, v3
	v_add_u32_e32 v154, v170, v16
	v_add_u32_e32 v160, v171, v3
	v_add_u32_e32 v158, v172, v16
	v_mad_i64_i32 v[134:135], s[30:31], v113, s55, v[18:19]
	v_mad_i64_i32 v[136:137], s[30:31], v111, s55, v[18:19]
	v_mad_i64_i32 v[138:139], s[30:31], v138, s55, v[18:19]
	v_mad_i64_i32 v[140:141], s[30:31], v140, s55, v[18:19]
	v_mad_i64_i32 v[142:143], s[30:31], v142, s55, v[18:19]
	v_mad_i64_i32 v[144:145], s[30:31], v144, s55, v[18:19]
	v_mad_i64_i32 v[146:147], s[30:31], v146, s55, v[18:19]
	v_mad_i64_i32 v[148:149], s[30:31], v148, s55, v[18:19]
	v_mad_i64_i32 v[150:151], s[30:31], v150, s55, v[18:19]
	v_mad_i64_i32 v[152:153], s[30:31], v152, s55, v[18:19]
	v_mad_i64_i32 v[154:155], s[30:31], v154, s55, v[18:19]
	v_mad_i64_i32 v[156:157], s[30:31], v156, s55, v[18:19]
	v_mad_i64_i32 v[158:159], s[30:31], v158, s55, v[18:19]
	v_mad_i64_i32 v[160:161], s[30:31], v160, s55, v[18:19]
	global_load_dword v111, v[130:131], off nt
	global_load_dword v113, v[132:133], off nt
	global_load_dword v173, v[134:135], off nt
	global_load_dword v174, v[136:137], off nt
	global_load_dword v175, v[138:139], off nt
	global_load_dword v176, v[140:141], off nt
	global_load_dword v177, v[142:143], off nt
	global_load_dword v178, v[144:145], off nt
	global_load_dword v179, v[146:147], off nt
	global_load_dword v180, v[148:149], off nt
	global_load_dword v181, v[150:151], off nt
	global_load_dword v182, v[152:153], off nt
	global_load_dword v183, v[154:155], off nt
	global_load_dword v184, v[156:157], off nt
	global_load_dword v185, v[158:159], off nt
	global_load_dword v186, v[160:161], off nt
	s_add_i32 s27, s27, 16
	s_add_i32 s26, s26, 16
	s_add_i32 s28, s28, -16
	v_mad_u64_u32 v[130:131], s[30:31], v109, s33, v[6:7]
	v_mad_u64_u32 v[132:133], s[30:31], v104, s33, v[6:7]
	v_mad_u64_u32 v[134:135], s[30:31], v117, s33, v[6:7]
	v_mad_u64_u32 v[136:137], s[30:31], v115, s33, v[6:7]
	v_mad_u64_u32 v[138:139], s[30:31], v162, s33, v[6:7]
	v_mad_u64_u32 v[140:141], s[30:31], v129, s33, v[6:7]
	v_mad_u64_u32 v[142:143], s[30:31], v164, s33, v[6:7]
	v_mad_u64_u32 v[144:145], s[30:31], v163, s33, v[6:7]
	v_mad_u64_u32 v[146:147], s[30:31], v166, s33, v[6:7]
	v_mad_u64_u32 v[148:149], s[30:31], v165, s33, v[6:7]
	v_mad_u64_u32 v[150:151], s[30:31], v168, s33, v[6:7]
	v_mad_u64_u32 v[152:153], s[30:31], v167, s33, v[6:7]
	v_mad_u64_u32 v[154:155], s[30:31], v170, s33, v[6:7]
	v_mad_u64_u32 v[156:157], s[30:31], v169, s33, v[6:7]
	v_mad_u64_u32 v[158:159], s[30:31], v172, s33, v[6:7]
	v_mad_u64_u32 v[160:161], s[30:31], v171, s33, v[6:7]
	s_lshl_b32 s29, s26, 1
	s_lshl_b32 s30, s27, 1
	v_or_b32_e32 v4, s29, v1
	v_or_b32_e32 v9, s30, v2
	s_add_i32 s31, s29, 4
	s_add_i32 s34, s30, 4
	s_add_i32 s35, s29, 8
	s_add_i32 s36, s30, 8
	s_add_i32 s37, s29, 12
	s_add_i32 s58, s30, 12
	s_add_i32 s59, s29, 16
	s_add_i32 s60, s30, 16
	s_add_i32 s61, s29, 20
	s_add_i32 s62, s30, 20
	s_add_i32 s63, s29, 24
	s_add_i32 s64, s30, 24
	s_add_i32 s29, s29, 28
	s_add_i32 s30, s30, 28
	v_add_u32_e32 v11, v4, v3
	v_add_u32_e32 v13, v9, v16
	v_or_b32_e32 v15, s31, v1
	v_or_b32_e32 v17, s34, v2
	v_or_b32_e32 v29, s35, v1
	v_or_b32_e32 v62, s36, v2
	v_or_b32_e32 v63, s37, v1
	v_or_b32_e32 v64, s58, v2
	v_or_b32_e32 v65, s59, v1
	v_or_b32_e32 v66, s60, v2
	v_or_b32_e32 v67, s61, v1
	v_or_b32_e32 v68, s62, v2
	v_or_b32_e32 v69, s63, v1
	v_or_b32_e32 v70, s64, v2
	v_or_b32_e32 v71, s29, v1
	v_or_b32_e32 v72, s30, v2
	v_mad_i64_i32 v[30:31], s[30:31], v13, s55, v[18:19]
	v_mad_i64_i32 v[32:33], s[30:31], v11, s55, v[18:19]
	v_add_u32_e32 v11, v15, v3
	v_add_u32_e32 v13, v17, v16
	v_add_u32_e32 v40, v29, v3
	v_add_u32_e32 v38, v62, v16
	v_add_u32_e32 v44, v63, v3
	v_add_u32_e32 v42, v64, v16
	v_add_u32_e32 v48, v65, v3
	v_add_u32_e32 v46, v66, v16
	v_add_u32_e32 v52, v67, v3
	v_add_u32_e32 v50, v68, v16
	v_add_u32_e32 v56, v69, v3
	v_add_u32_e32 v54, v70, v16
	v_add_u32_e32 v60, v71, v3
	v_add_u32_e32 v58, v72, v16
	v_mad_i64_i32 v[34:35], s[30:31], v13, s55, v[18:19]
	v_mad_i64_i32 v[36:37], s[30:31], v11, s55, v[18:19]
	v_mad_i64_i32 v[38:39], s[30:31], v38, s55, v[18:19]
	v_mad_i64_i32 v[40:41], s[30:31], v40, s55, v[18:19]
	v_mad_i64_i32 v[42:43], s[30:31], v42, s55, v[18:19]
	v_mad_i64_i32 v[44:45], s[30:31], v44, s55, v[18:19]
	v_mad_i64_i32 v[46:47], s[30:31], v46, s55, v[18:19]
	v_mad_i64_i32 v[48:49], s[30:31], v48, s55, v[18:19]
	v_mad_i64_i32 v[50:51], s[30:31], v50, s55, v[18:19]
	v_mad_i64_i32 v[52:53], s[30:31], v52, s55, v[18:19]
	v_mad_i64_i32 v[54:55], s[30:31], v54, s55, v[18:19]
	v_mad_i64_i32 v[56:57], s[30:31], v56, s55, v[18:19]
	v_mad_i64_i32 v[58:59], s[30:31], v58, s55, v[18:19]
	v_mad_i64_i32 v[60:61], s[30:31], v60, s55, v[18:19]
	global_load_dword v11, v[30:31], off nt
	global_load_dword v13, v[32:33], off nt
	global_load_dword v73, v[34:35], off nt
	global_load_dword v74, v[36:37], off nt
	global_load_dword v75, v[38:39], off nt
	global_load_dword v76, v[40:41], off nt
	global_load_dword v77, v[42:43], off nt
	global_load_dword v78, v[44:45], off nt
	global_load_dword v79, v[46:47], off nt
	global_load_dword v80, v[48:49], off nt
	global_load_dword v81, v[50:51], off nt
	global_load_dword v82, v[52:53], off nt
	global_load_dword v83, v[54:55], off nt
	global_load_dword v84, v[56:57], off nt
	global_load_dword v85, v[58:59], off nt
	global_load_dword v86, v[60:61], off nt
	s_add_i32 s27, s27, 16
	s_add_i32 s26, s26, 16
	s_add_i32 s28, s28, -16
	v_mad_u64_u32 v[30:31], s[30:31], v9, s33, v[6:7]
	v_mad_u64_u32 v[32:33], s[30:31], v4, s33, v[6:7]
	v_mad_u64_u32 v[34:35], s[30:31], v17, s33, v[6:7]
	v_mad_u64_u32 v[36:37], s[30:31], v15, s33, v[6:7]
	v_mad_u64_u32 v[38:39], s[30:31], v62, s33, v[6:7]
	v_mad_u64_u32 v[40:41], s[30:31], v29, s33, v[6:7]
	v_mad_u64_u32 v[42:43], s[30:31], v64, s33, v[6:7]
	v_mad_u64_u32 v[44:45], s[30:31], v63, s33, v[6:7]
	v_mad_u64_u32 v[46:47], s[30:31], v66, s33, v[6:7]
	v_mad_u64_u32 v[48:49], s[30:31], v65, s33, v[6:7]
	v_mad_u64_u32 v[50:51], s[30:31], v68, s33, v[6:7]
	v_mad_u64_u32 v[52:53], s[30:31], v67, s33, v[6:7]
	v_mad_u64_u32 v[54:55], s[30:31], v70, s33, v[6:7]
	v_mad_u64_u32 v[56:57], s[30:31], v69, s33, v[6:7]
	v_mad_u64_u32 v[58:59], s[30:31], v72, s33, v[6:7]
	v_mad_u64_u32 v[60:61], s[30:31], v71, s33, v[6:7]
	s_waitcnt vmcnt(31)
	ds_write_b32 v130, v111
	s_waitcnt vmcnt(30)
	ds_write_b32 v132, v113
	s_waitcnt vmcnt(29)
	ds_write_b32 v134, v173
	s_waitcnt vmcnt(28)
	ds_write_b32 v136, v174
	s_waitcnt vmcnt(27)
	ds_write_b32 v138, v175
	s_waitcnt vmcnt(26)
	ds_write_b32 v140, v176
	s_waitcnt vmcnt(25)
	ds_write_b32 v142, v177
	s_waitcnt vmcnt(24)
	ds_write_b32 v144, v178
	s_waitcnt vmcnt(23)
	ds_write_b32 v146, v179
	s_waitcnt vmcnt(22)
	ds_write_b32 v148, v180
	s_waitcnt vmcnt(21)
	ds_write_b32 v150, v181
	s_waitcnt vmcnt(20)
	ds_write_b32 v152, v182
	s_waitcnt vmcnt(19)
	ds_write_b32 v154, v183
	s_waitcnt vmcnt(18)
	ds_write_b32 v156, v184
	s_waitcnt vmcnt(17)
	ds_write_b32 v158, v185
	s_waitcnt vmcnt(16)
	ds_write_b32 v160, v186
	s_waitcnt vmcnt(15)
	ds_write_b32 v30, v11
	s_waitcnt vmcnt(14)
	ds_write_b32 v32, v13
	s_waitcnt vmcnt(13)
	ds_write_b32 v34, v73
	s_waitcnt vmcnt(12)
	ds_write_b32 v36, v74
	s_waitcnt vmcnt(11)
	ds_write_b32 v38, v75
	s_waitcnt vmcnt(10)
	ds_write_b32 v40, v76
	s_waitcnt vmcnt(9)
	ds_write_b32 v42, v77
	s_waitcnt vmcnt(8)
	ds_write_b32 v44, v78
	s_waitcnt vmcnt(7)
	ds_write_b32 v46, v79
	s_waitcnt vmcnt(6)
	ds_write_b32 v48, v80
	s_waitcnt vmcnt(5)
	ds_write_b32 v50, v81
	s_waitcnt vmcnt(4)
	ds_write_b32 v52, v82
	s_waitcnt vmcnt(3)
	ds_write_b32 v54, v83
	s_waitcnt vmcnt(2)
	ds_write_b32 v56, v84
	s_waitcnt vmcnt(1)
	ds_write_b32 v58, v85
	s_waitcnt vmcnt(0)
	ds_write_b32 v60, v86
	s_waitcnt lgkmcnt(0)
	ds_read2_b32 v[30:31], v22 offset1:8
	ds_read2_b32 v[32:33], v22 offset0:33 offset1:41
	ds_read2_b32 v[34:35], v22 offset0:66 offset1:74
	ds_read2_b32 v[36:37], v22 offset0:99 offset1:107
	v_mov_b64_e32 v[18:19], s[18:19]
	s_waitcnt lgkmcnt(3)
	v_bfe_u32 v3, v30, 16, 1
	v_add3_u32 v3, v30, v3, s45
	s_waitcnt lgkmcnt(2)
	v_bfe_u32 v4, v32, 16, 1
	ds_read2_b32 v[38:39], v22 offset0:132 offset1:140
	v_mad_i64_i32 v[12:13], s[26:27], v12, s56, v[18:19]
	v_ashrrev_i32_e32 v17, 31, v16
	v_lshrrev_b32_e32 v3, 16, v3
	v_add3_u32 v4, v32, v4, s45
	ds_read2_b32 v[40:41], v22 offset0:165 offset1:173
	v_lshl_add_u64 v[12:13], v[16:17], 1, v[12:13]
	v_and_or_b32 v16, v4, s46, v3
	s_waitcnt lgkmcnt(3)
	v_bfe_u32 v3, v34, 16, 1
	v_add3_u32 v3, v34, v3, s45
	s_waitcnt lgkmcnt(2)
	v_bfe_u32 v4, v36, 16, 1
	ds_read2_b32 v[42:43], v22 offset0:198 offset1:206
	v_lshrrev_b32_e32 v3, 16, v3
	v_add3_u32 v4, v36, v4, s45
	ds_read2_b32 v[44:45], v22 offset0:231 offset1:239
	v_and_or_b32 v17, v4, s46, v3
	s_waitcnt lgkmcnt(3)
	v_bfe_u32 v3, v38, 16, 1
	v_add3_u32 v3, v38, v3, s45
	s_waitcnt lgkmcnt(2)
	v_bfe_u32 v4, v40, 16, 1
	v_lshrrev_b32_e32 v3, 16, v3
	v_add3_u32 v4, v40, v4, s45
	v_and_or_b32 v18, v4, s46, v3
	s_waitcnt lgkmcnt(1)
	v_bfe_u32 v3, v42, 16, 1
	v_add3_u32 v3, v42, v3, s45
	s_waitcnt lgkmcnt(0)
	v_bfe_u32 v4, v44, 16, 1
	v_lshrrev_b32_e32 v3, 16, v3
	v_add3_u32 v4, v44, v4, s45
	v_or_b32_e32 v46, v14, v21
	v_mov_b32_e32 v11, v5
	v_and_or_b32 v19, v4, s46, v3
	v_ashrrev_i32_e32 v47, 31, v46
	v_bfe_u32 v3, v31, 16, 1
	v_lshl_add_u64 v[12:13], v[12:13], 0, v[10:11]
	v_lshlrev_b64 v[46:47], 12, v[46:47]
	v_add3_u32 v3, v31, v3, s45
	v_bfe_u32 v4, v33, 16, 1
	v_lshl_add_u64 v[46:47], v[12:13], 0, v[46:47]
	v_lshrrev_b32_e32 v3, 16, v3
	v_add3_u32 v4, v33, v4, s45
	global_store_dwordx4 v[46:47], v[16:19], off nt
	v_or_b32_e32 v30, v14, v23
	v_ashrrev_i32_e32 v31, 31, v30
	v_and_or_b32 v16, v4, s46, v3
	v_bfe_u32 v3, v35, 16, 1
	v_add3_u32 v3, v35, v3, s45
	v_bfe_u32 v4, v37, 16, 1
	v_lshrrev_b32_e32 v3, 16, v3
	v_add3_u32 v4, v37, v4, s45
	v_and_or_b32 v17, v4, s46, v3
	v_bfe_u32 v3, v39, 16, 1
	v_add3_u32 v3, v39, v3, s45
	v_bfe_u32 v4, v41, 16, 1
	v_lshrrev_b32_e32 v3, 16, v3
	v_add3_u32 v4, v41, v4, s45
	v_and_or_b32 v18, v4, s46, v3
	v_bfe_u32 v3, v43, 16, 1
	v_add3_u32 v3, v43, v3, s45
	v_bfe_u32 v4, v45, 16, 1
	v_lshrrev_b32_e32 v3, 16, v3
	v_add3_u32 v4, v45, v4, s45
	v_lshlrev_b64 v[30:31], 12, v[30:31]
	v_and_or_b32 v19, v4, s46, v3
	ds_read2_b32 v[32:33], v22 offset0:16 offset1:24
	v_lshl_add_u64 v[30:31], v[12:13], 0, v[30:31]
	global_store_dwordx4 v[30:31], v[16:19], off nt
	ds_read2_b32 v[30:31], v22 offset0:49 offset1:57
	ds_read2_b32 v[34:35], v22 offset0:82 offset1:90
	ds_read2_b32 v[36:37], v22 offset0:115 offset1:123
	s_waitcnt lgkmcnt(3)
	v_bfe_u32 v3, v32, 16, 1
	v_add3_u32 v3, v32, v3, s45
	s_waitcnt lgkmcnt(2)
	v_bfe_u32 v4, v30, 16, 1
	ds_read2_b32 v[38:39], v22 offset0:148 offset1:156
	v_lshrrev_b32_e32 v3, 16, v3
	v_add3_u32 v4, v30, v4, s45
	ds_read2_b32 v[40:41], v22 offset0:181 offset1:189
	v_and_or_b32 v16, v4, s46, v3
	s_waitcnt lgkmcnt(3)
	v_bfe_u32 v3, v34, 16, 1
	v_add3_u32 v3, v34, v3, s45
	s_waitcnt lgkmcnt(2)
	v_bfe_u32 v4, v36, 16, 1
	ds_read2_b32 v[42:43], v22 offset0:214 offset1:222
	v_lshrrev_b32_e32 v3, 16, v3
	v_add3_u32 v4, v36, v4, s45
	ds_read2_b32 v[44:45], v22 offset0:247 offset1:255
	v_and_or_b32 v17, v4, s46, v3
	s_waitcnt lgkmcnt(3)
	v_bfe_u32 v3, v38, 16, 1
	v_add3_u32 v3, v38, v3, s45
	s_waitcnt lgkmcnt(2)
	v_bfe_u32 v4, v40, 16, 1
	v_lshrrev_b32_e32 v3, 16, v3
	v_add3_u32 v4, v40, v4, s45
	v_and_or_b32 v18, v4, s46, v3
	s_waitcnt lgkmcnt(1)
	v_bfe_u32 v3, v42, 16, 1
	v_add3_u32 v3, v42, v3, s45
	s_waitcnt lgkmcnt(0)
	v_bfe_u32 v4, v44, 16, 1
	v_lshrrev_b32_e32 v3, 16, v3
	v_add3_u32 v4, v44, v4, s45
	v_or_b32_e32 v46, v14, v24
	v_and_or_b32 v19, v4, s46, v3
	v_ashrrev_i32_e32 v47, 31, v46
	v_bfe_u32 v3, v33, 16, 1
	v_lshlrev_b64 v[46:47], 12, v[46:47]
	v_add3_u32 v3, v33, v3, s45
	v_bfe_u32 v4, v31, 16, 1
	v_lshl_add_u64 v[46:47], v[12:13], 0, v[46:47]
	v_lshrrev_b32_e32 v3, 16, v3
	v_add3_u32 v4, v31, v4, s45
	global_store_dwordx4 v[46:47], v[16:19], off nt
	v_or_b32_e32 v14, v14, v25
	v_ashrrev_i32_e32 v15, 31, v14
	v_and_or_b32 v16, v4, s46, v3
	v_bfe_u32 v3, v35, 16, 1
	v_add3_u32 v3, v35, v3, s45
	v_bfe_u32 v4, v37, 16, 1
	v_lshrrev_b32_e32 v3, 16, v3
	v_add3_u32 v4, v37, v4, s45
	v_and_or_b32 v17, v4, s46, v3
	v_bfe_u32 v3, v39, 16, 1
	v_add3_u32 v3, v39, v3, s45
	v_bfe_u32 v4, v41, 16, 1
	v_lshrrev_b32_e32 v3, 16, v3
	v_add3_u32 v4, v41, v4, s45
	v_and_or_b32 v18, v4, s46, v3
	v_bfe_u32 v3, v43, 16, 1
	v_add3_u32 v3, v43, v3, s45
	v_bfe_u32 v4, v45, 16, 1
	v_lshrrev_b32_e32 v3, 16, v3
	v_add3_u32 v4, v45, v4, s45
	v_lshlrev_b64 v[14:15], 12, v[14:15]
	v_and_or_b32 v19, v4, s46, v3
	v_lshl_add_u64 v[12:13], v[12:13], 0, v[14:15]
	global_store_dwordx4 v[12:13], v[16:19], off nt
	s_waitcnt lgkmcnt(0)
	s_branch .LBB0_105
